# nt on GEMM1 epilogue stores (keeps A/B stream resident in L2/MALL)
# speedup vs baseline: 1.0229x; 1.0168x over previous
; __device__ __forceinline__ float sigmoidf_(float x) { return __builtin_amdgcn_rcpf(1.f + __expf(-x)); }
;     __device__ __forceinline__ void operator()(const f32x4 (&acc)[2][2][4][2], const Unit& u, int wr, int wc, int fr, int fq) const {
;     ...
;             const int ti = u.pn >> 1, c0 = 128 * (ti >> 1) + 32 * wc + 8 * fq;
;             h16* dst = (ti & 1) ? PGG : PP;
; #pragma unroll
;             for (int ai = 0; ai < 2; ++ai)
; #pragma unroll
;                 for (int m = 0; m < 4; ++m) { const size_t off = (size_t)(row0 + ai * HALF + m * 16) * HW + c0;
;                     float o[8];
;                     if (ti & 1) {
; #pragma unroll
;                         for (int n = 0; n < 2; ++n)
; #pragma unroll
;                             for (int j = 0; j < 4; ++j) { const float g = acc[ai][1][m][n][j]; o[4 * n + j] = acc[ai][0][m][n][j] * g * sigmoidf_(g); }
;                     } else {
; #pragma unroll
;                         for (int n = 0; n < 2; ++n)
; #pragma unroll
;                             for (int j = 0; j < 4; ++j) o[4 * n + j] = acc[ai][0][m][n][j] * acc[ai][1][m][n][j];
;                     }
;                     u32x4 w; w.x = pkh(o[0], o[1]); w.y = pkh(o[2], o[3]); w.z = pkh(o[4], o[5]); w.w = pkh(o[6], o[7]);
;                     *(u32x4*)(dst + off) = w; }
.LBB0_109:
	s_and_b32 s27, s18, 0x7fffffc
	s_or_b32 s27, s27, s63
	s_and_b64 s[4:5], exec, s[4:5]
	s_cselect_b32 s4, s70, 0x26200000
	v_lshl_or_b32 v144, s27, 5, v159
	s_add_u32 s4, s4, s53
	s_addc_u32 s5, s7, 0
	v_ashrrev_i32_e32 v145, 31, v144
	v_ashrrev_i32_e32 v143, 31, v142
	v_lshl_add_u64 v[144:145], v[144:145], 1, s[4:5]
	v_cvt_pk_f16_f32 v147, v148, v149
	v_cvt_pk_f16_f32 v149, v150, v151
	v_lshlrev_b64 v[150:151], 12, v[142:143]
	v_cvt_pk_f16_f32 v146, v152, v153
	v_cvt_pk_f16_f32 v148, v154, v155
	v_lshl_add_u64 v[150:151], v[144:145], 0, v[150:151]
	global_store_dwordx4 v[150:151], v[146:149], off nt
	s_mov_b64 s[48:49], -1
	s_andn2_b64 vcc, exec, s[46:47]
	v_cndmask_b32_e64 v146, 0, 1, s[46:47]
	v_cmp_ne_u32_e64 s[4:5], 1, v146
	v_pk_mul_f32 v[148:149], v[116:117], v[92:93]
	v_pk_mul_f32 v[146:147], v[112:113], v[88:89]
	s_cbranch_vccnz .LBB0_111
	v_mul_f32_e32 v151, 0xbfb8aa3b, v93
	v_exp_f32_e32 v151, v151
	v_mul_f32_e32 v153, 0xbfb8aa3b, v95
	v_exp_f32_e32 v154, v153
	v_mul_f32_e32 v150, 0xbfb8aa3b, v92
	v_add_f32_e32 v151, 1.0, v151
	v_rcp_f32_e32 v153, v151
	v_add_f32_e32 v151, 1.0, v154
	v_mul_f32_e32 v154, 0xbfb8aa3b, v88
	v_exp_f32_e32 v154, v154
	v_mul_f32_e32 v155, 0xbfb8aa3b, v89
	v_exp_f32_e32 v150, v150
	v_exp_f32_e32 v155, v155
	v_add_f32_e32 v154, 1.0, v154
	v_rcp_f32_e32 v156, v154
	v_add_f32_e32 v150, 1.0, v150
	v_add_f32_e32 v154, 1.0, v155
	v_mul_f32_e32 v155, 0xbfb8aa3b, v90
	v_rcp_f32_e32 v152, v150
	v_mul_f32_e32 v150, 0xbfb8aa3b, v94
	v_exp_f32_e32 v155, v155
	v_mul_f32_e32 v157, 0xbfb8aa3b, v91
	v_exp_f32_e32 v150, v150
	v_exp_f32_e32 v165, v157
	v_rcp_f32_e32 v157, v154
	v_add_f32_e32 v154, 1.0, v155
	v_add_f32_e32 v150, 1.0, v150
	v_rcp_f32_e32 v164, v154
	v_add_f32_e32 v154, 1.0, v165
	v_rcp_f32_e32 v150, v150
	v_rcp_f32_e32 v151, v151
	v_rcp_f32_e32 v165, v154
	v_pk_mul_f32 v[154:155], v[118:119], v[94:95]
	v_pk_mul_f32 v[166:167], v[114:115], v[90:91]
	v_pk_mul_f32 v[150:151], v[154:155], v[150:151]
	v_pk_mul_f32 v[154:155], v[148:149], v[152:153]
	v_pk_mul_f32 v[152:153], v[166:167], v[164:165]
	v_pk_mul_f32 v[156:157], v[146:147], v[156:157]
	s_mov_b64 s[48:49], 0

; __device__ __forceinline__ float sigmoidf_(float x) { return __builtin_amdgcn_rcpf(1.f + __expf(-x)); }
;     __device__ __forceinline__ void operator()(const f32x4 (&acc)[2][2][4][2], const Unit& u, int wr, int wc, int fr, int fq) const {
;     ...
;             for (int ai = 0; ai < 2; ++ai)
; #pragma unroll
;                 for (int m = 0; m < 4; ++m) { const size_t off = (size_t)(row0 + ai * HALF + m * 16) * HW + c0;
;                     float o[8];
;                     if (ti & 1) {
; #pragma unroll
;                         for (int n = 0; n < 2; ++n)
; #pragma unroll
;                             for (int j = 0; j < 4; ++j) { const float g = acc[ai][1][m][n][j]; o[4 * n + j] = acc[ai][0][m][n][j] * g * sigmoidf_(g); }
;                     } else {
; #pragma unroll
;                         for (int n = 0; n < 2; ++n)
; #pragma unroll
;                             for (int j = 0; j < 4; ++j) o[4 * n + j] = acc[ai][0][m][n][j] * acc[ai][1][m][n][j];
;                     }
;                     u32x4 w; w.x = pkh(o[0], o[1]); w.y = pkh(o[2], o[3]); w.z = pkh(o[4], o[5]); w.w = pkh(o[6], o[7]);
;                     *(u32x4*)(dst + off) = w; }
.LBB0_113:
	v_or_b32_e32 v164, 16, v142
	v_ashrrev_i32_e32 v165, 31, v164
	v_cvt_pk_f16_f32 v147, v150, v151
	v_lshlrev_b64 v[150:151], 12, v[164:165]
	v_cvt_pk_f16_f32 v146, v154, v155
	v_cvt_pk_f16_f32 v148, v156, v157
	v_cvt_pk_f16_f32 v149, v152, v153
	v_lshl_add_u64 v[150:151], v[144:145], 0, v[150:151]
	global_store_dwordx4 v[150:151], v[146:149], off nt
	s_mov_b64 s[46:47], -1
	s_and_b64 vcc, exec, s[4:5]
	v_pk_mul_f32 v[148:149], v[100:101], v[76:77]
	v_pk_mul_f32 v[146:147], v[96:97], v[72:73]
	s_cbranch_vccnz .LBB0_115
	v_mul_f32_e32 v151, 0xbfb8aa3b, v77
	v_exp_f32_e32 v151, v151
	v_mul_f32_e32 v153, 0xbfb8aa3b, v79
	v_exp_f32_e32 v154, v153
	v_mul_f32_e32 v150, 0xbfb8aa3b, v76
	v_add_f32_e32 v151, 1.0, v151
	v_rcp_f32_e32 v153, v151
	v_add_f32_e32 v151, 1.0, v154
	v_mul_f32_e32 v154, 0xbfb8aa3b, v72
	v_exp_f32_e32 v154, v154
	v_mul_f32_e32 v155, 0xbfb8aa3b, v73
	v_exp_f32_e32 v150, v150
	v_exp_f32_e32 v155, v155
	v_add_f32_e32 v154, 1.0, v154
	v_rcp_f32_e32 v156, v154
	v_add_f32_e32 v150, 1.0, v150
	v_add_f32_e32 v154, 1.0, v155
	v_mul_f32_e32 v155, 0xbfb8aa3b, v74
	v_rcp_f32_e32 v152, v150
	v_mul_f32_e32 v150, 0xbfb8aa3b, v78
	v_exp_f32_e32 v155, v155
	v_mul_f32_e32 v157, 0xbfb8aa3b, v75
	v_exp_f32_e32 v150, v150
	v_exp_f32_e32 v165, v157
	v_rcp_f32_e32 v157, v154
	v_add_f32_e32 v154, 1.0, v155
	v_add_f32_e32 v150, 1.0, v150
	v_rcp_f32_e32 v164, v154
	v_add_f32_e32 v154, 1.0, v165
	v_rcp_f32_e32 v150, v150
	v_rcp_f32_e32 v151, v151
	v_rcp_f32_e32 v165, v154
	v_pk_mul_f32 v[154:155], v[102:103], v[78:79]
	v_pk_mul_f32 v[166:167], v[98:99], v[74:75]
	v_pk_mul_f32 v[150:151], v[154:155], v[150:151]
	v_pk_mul_f32 v[154:155], v[148:149], v[152:153]
	v_pk_mul_f32 v[152:153], v[166:167], v[164:165]
	v_pk_mul_f32 v[156:157], v[146:147], v[156:157]
	s_mov_b64 s[46:47], 0

; __device__ __forceinline__ float sigmoidf_(float x) { return __builtin_amdgcn_rcpf(1.f + __expf(-x)); }
;     __device__ __forceinline__ void operator()(const f32x4 (&acc)[2][2][4][2], const Unit& u, int wr, int wc, int fr, int fq) const {
;     ...
;             for (int ai = 0; ai < 2; ++ai)
; #pragma unroll
;                 for (int m = 0; m < 4; ++m) { const size_t off = (size_t)(row0 + ai * HALF + m * 16) * HW + c0;
;                     float o[8];
;                     if (ti & 1) {
; #pragma unroll
;                         for (int n = 0; n < 2; ++n)
; #pragma unroll
;                             for (int j = 0; j < 4; ++j) { const float g = acc[ai][1][m][n][j]; o[4 * n + j] = acc[ai][0][m][n][j] * g * sigmoidf_(g); }
;                     } else {
; #pragma unroll
;                         for (int n = 0; n < 2; ++n)
; #pragma unroll
;                             for (int j = 0; j < 4; ++j) o[4 * n + j] = acc[ai][0][m][n][j] * acc[ai][1][m][n][j];
;                     }
;                     u32x4 w; w.x = pkh(o[0], o[1]); w.y = pkh(o[2], o[3]); w.z = pkh(o[4], o[5]); w.w = pkh(o[6], o[7]);
;                     *(u32x4*)(dst + off) = w; }
.LBB0_117:
	v_or_b32_e32 v164, 32, v142
	v_ashrrev_i32_e32 v165, 31, v164
	v_cvt_pk_f16_f32 v147, v150, v151
	v_lshlrev_b64 v[150:151], 12, v[164:165]
	v_cvt_pk_f16_f32 v146, v154, v155
	v_cvt_pk_f16_f32 v148, v156, v157
	v_cvt_pk_f16_f32 v149, v152, v153
	v_lshl_add_u64 v[150:151], v[144:145], 0, v[150:151]
	global_store_dwordx4 v[150:151], v[146:149], off nt
	s_mov_b64 s[46:47], -1
	s_and_b64 vcc, exec, s[4:5]
	v_pk_mul_f32 v[148:149], v[84:85], v[68:69]
	v_pk_mul_f32 v[146:147], v[80:81], v[64:65]
	s_cbranch_vccnz .LBB0_119
	v_mul_f32_e32 v151, 0xbfb8aa3b, v69
	v_exp_f32_e32 v151, v151
	v_mul_f32_e32 v153, 0xbfb8aa3b, v71
	v_exp_f32_e32 v154, v153
	v_mul_f32_e32 v150, 0xbfb8aa3b, v68
	v_add_f32_e32 v151, 1.0, v151
	v_rcp_f32_e32 v153, v151
	v_add_f32_e32 v151, 1.0, v154
	v_mul_f32_e32 v154, 0xbfb8aa3b, v64
	v_exp_f32_e32 v154, v154
	v_mul_f32_e32 v155, 0xbfb8aa3b, v65
	v_exp_f32_e32 v150, v150
	v_exp_f32_e32 v155, v155
	v_add_f32_e32 v154, 1.0, v154
	v_rcp_f32_e32 v156, v154
	v_add_f32_e32 v150, 1.0, v150
	v_add_f32_e32 v154, 1.0, v155
	v_mul_f32_e32 v155, 0xbfb8aa3b, v66
	v_rcp_f32_e32 v152, v150
	v_mul_f32_e32 v150, 0xbfb8aa3b, v70
	v_exp_f32_e32 v155, v155
	v_mul_f32_e32 v157, 0xbfb8aa3b, v67
	v_exp_f32_e32 v150, v150
	v_exp_f32_e32 v165, v157
	v_rcp_f32_e32 v157, v154
	v_add_f32_e32 v154, 1.0, v155
	v_add_f32_e32 v150, 1.0, v150
	v_rcp_f32_e32 v164, v154
	v_add_f32_e32 v154, 1.0, v165
	v_rcp_f32_e32 v150, v150
	v_rcp_f32_e32 v151, v151
	v_rcp_f32_e32 v165, v154
	v_pk_mul_f32 v[154:155], v[86:87], v[70:71]
	v_pk_mul_f32 v[166:167], v[82:83], v[66:67]
	v_pk_mul_f32 v[150:151], v[154:155], v[150:151]
	v_pk_mul_f32 v[154:155], v[148:149], v[152:153]
	v_pk_mul_f32 v[152:153], v[166:167], v[164:165]
	v_pk_mul_f32 v[156:157], v[146:147], v[156:157]
	s_mov_b64 s[46:47], 0

; __device__ __forceinline__ float sigmoidf_(float x) { return __builtin_amdgcn_rcpf(1.f + __expf(-x)); }
;     __device__ __forceinline__ void operator()(const f32x4 (&acc)[2][2][4][2], const Unit& u, int wr, int wc, int fr, int fq) const {
;     ...
;             for (int ai = 0; ai < 2; ++ai)
; #pragma unroll
;                 for (int m = 0; m < 4; ++m) { const size_t off = (size_t)(row0 + ai * HALF + m * 16) * HW + c0;
;                     float o[8];
;                     if (ti & 1) {
; #pragma unroll
;                         for (int n = 0; n < 2; ++n)
; #pragma unroll
;                             for (int j = 0; j < 4; ++j) { const float g = acc[ai][1][m][n][j]; o[4 * n + j] = acc[ai][0][m][n][j] * g * sigmoidf_(g); }
;                     } else {
; #pragma unroll
;                         for (int n = 0; n < 2; ++n)
; #pragma unroll
;                             for (int j = 0; j < 4; ++j) o[4 * n + j] = acc[ai][0][m][n][j] * acc[ai][1][m][n][j];
;                     }
;                     u32x4 w; w.x = pkh(o[0], o[1]); w.y = pkh(o[2], o[3]); w.z = pkh(o[4], o[5]); w.w = pkh(o[6], o[7]);
;                     *(u32x4*)(dst + off) = w; }
.LBB0_121:
	v_or_b32_e32 v164, 48, v142
	v_ashrrev_i32_e32 v165, 31, v164
	v_cvt_pk_f16_f32 v147, v150, v151
	v_lshlrev_b64 v[150:151], 12, v[164:165]
	v_cvt_pk_f16_f32 v146, v154, v155
	v_cvt_pk_f16_f32 v148, v156, v157
	v_cvt_pk_f16_f32 v149, v152, v153
	v_lshl_add_u64 v[150:151], v[144:145], 0, v[150:151]
	global_store_dwordx4 v[150:151], v[146:149], off nt
	s_mov_b64 s[46:47], -1
	s_and_b64 vcc, exec, s[4:5]
	v_pk_mul_f32 v[148:149], v[60:61], v[44:45]
	v_pk_mul_f32 v[146:147], v[56:57], v[40:41]
	s_cbranch_vccnz .LBB0_123
	v_mul_f32_e32 v151, 0xbfb8aa3b, v45
	v_exp_f32_e32 v151, v151
	v_mul_f32_e32 v153, 0xbfb8aa3b, v47
	v_exp_f32_e32 v154, v153
	v_mul_f32_e32 v150, 0xbfb8aa3b, v44
	v_add_f32_e32 v151, 1.0, v151
	v_rcp_f32_e32 v153, v151
	v_add_f32_e32 v151, 1.0, v154
	v_mul_f32_e32 v154, 0xbfb8aa3b, v40
	v_exp_f32_e32 v154, v154
	v_mul_f32_e32 v155, 0xbfb8aa3b, v41
	v_exp_f32_e32 v150, v150
	v_exp_f32_e32 v155, v155
	v_add_f32_e32 v154, 1.0, v154
	v_rcp_f32_e32 v156, v154
	v_add_f32_e32 v150, 1.0, v150
	v_add_f32_e32 v154, 1.0, v155
	v_mul_f32_e32 v155, 0xbfb8aa3b, v42
	v_rcp_f32_e32 v152, v150
	v_mul_f32_e32 v150, 0xbfb8aa3b, v46
	v_exp_f32_e32 v155, v155
	v_mul_f32_e32 v157, 0xbfb8aa3b, v43
	v_exp_f32_e32 v150, v150
	v_exp_f32_e32 v165, v157
	v_rcp_f32_e32 v157, v154
	v_add_f32_e32 v154, 1.0, v155
	v_add_f32_e32 v150, 1.0, v150
	v_rcp_f32_e32 v164, v154
	v_add_f32_e32 v154, 1.0, v165
	v_rcp_f32_e32 v150, v150
	v_rcp_f32_e32 v151, v151
	v_rcp_f32_e32 v165, v154
	v_pk_mul_f32 v[154:155], v[62:63], v[46:47]
	v_pk_mul_f32 v[166:167], v[58:59], v[42:43]
	v_pk_mul_f32 v[150:151], v[154:155], v[150:151]
	v_pk_mul_f32 v[154:155], v[148:149], v[152:153]
	v_pk_mul_f32 v[152:153], v[166:167], v[164:165]
	v_pk_mul_f32 v[156:157], v[146:147], v[156:157]
	s_mov_b64 s[46:47], 0

; __device__ __forceinline__ float sigmoidf_(float x) { return __builtin_amdgcn_rcpf(1.f + __expf(-x)); }
;     __device__ __forceinline__ void operator()(const f32x4 (&acc)[2][2][4][2], const Unit& u, int wr, int wc, int fr, int fq) const {
;     ...
;             for (int ai = 0; ai < 2; ++ai)
; #pragma unroll
;                 for (int m = 0; m < 4; ++m) { const size_t off = (size_t)(row0 + ai * HALF + m * 16) * HW + c0;
;                     float o[8];
;                     if (ti & 1) {
; #pragma unroll
;                         for (int n = 0; n < 2; ++n)
; #pragma unroll
;                             for (int j = 0; j < 4; ++j) { const float g = acc[ai][1][m][n][j]; o[4 * n + j] = acc[ai][0][m][n][j] * g * sigmoidf_(g); }
;                     } else {
; #pragma unroll
;                         for (int n = 0; n < 2; ++n)
; #pragma unroll
;                             for (int j = 0; j < 4; ++j) o[4 * n + j] = acc[ai][0][m][n][j] * acc[ai][1][m][n][j];
;                     }
;                     u32x4 w; w.x = pkh(o[0], o[1]); w.y = pkh(o[2], o[3]); w.z = pkh(o[4], o[5]); w.w = pkh(o[6], o[7]);
;                     *(u32x4*)(dst + off) = w; }
.LBB0_125:
	v_lshlrev_b64 v[164:165], 12, v[142:143]
	v_cvt_pk_f16_f32 v147, v150, v151
	v_lshl_add_u64 v[150:151], v[144:145], 0, v[164:165]
	v_add_co_u32_e32 v150, vcc, 0x80000, v150
	v_cvt_pk_f16_f32 v146, v154, v155
	v_cvt_pk_f16_f32 v148, v156, v157
	v_cvt_pk_f16_f32 v149, v152, v153
	v_addc_co_u32_e32 v151, vcc, 0, v151, vcc
	global_store_dwordx4 v[150:151], v[146:149], off nt
	s_mov_b64 s[46:47], -1
	s_and_b64 vcc, exec, s[4:5]
	v_pk_mul_f32 v[148:149], v[52:53], v[28:29]
	v_pk_mul_f32 v[146:147], v[48:49], v[24:25]
	s_cbranch_vccnz .LBB0_127
	v_mul_f32_e32 v151, 0xbfb8aa3b, v29
	v_exp_f32_e32 v151, v151
	v_mul_f32_e32 v153, 0xbfb8aa3b, v31
	v_exp_f32_e32 v154, v153
	v_mul_f32_e32 v150, 0xbfb8aa3b, v28
	v_add_f32_e32 v151, 1.0, v151
	v_rcp_f32_e32 v153, v151
	v_add_f32_e32 v151, 1.0, v154
	v_mul_f32_e32 v154, 0xbfb8aa3b, v24
	v_exp_f32_e32 v154, v154
	v_mul_f32_e32 v155, 0xbfb8aa3b, v25
	v_exp_f32_e32 v150, v150
	v_exp_f32_e32 v155, v155
	v_add_f32_e32 v154, 1.0, v154
	v_rcp_f32_e32 v156, v154
	v_add_f32_e32 v150, 1.0, v150
	v_add_f32_e32 v154, 1.0, v155
	v_mul_f32_e32 v155, 0xbfb8aa3b, v26
	v_rcp_f32_e32 v152, v150
	v_mul_f32_e32 v150, 0xbfb8aa3b, v30
	v_exp_f32_e32 v155, v155
	v_mul_f32_e32 v157, 0xbfb8aa3b, v27
	v_exp_f32_e32 v150, v150
	v_exp_f32_e32 v165, v157
	v_rcp_f32_e32 v157, v154
	v_add_f32_e32 v154, 1.0, v155
	v_add_f32_e32 v150, 1.0, v150
	v_rcp_f32_e32 v164, v154
	v_add_f32_e32 v154, 1.0, v165
	v_rcp_f32_e32 v150, v150
	v_rcp_f32_e32 v151, v151
	v_rcp_f32_e32 v165, v154
	v_pk_mul_f32 v[154:155], v[54:55], v[30:31]
	v_pk_mul_f32 v[166:167], v[50:51], v[26:27]
	v_pk_mul_f32 v[150:151], v[154:155], v[150:151]
	v_pk_mul_f32 v[154:155], v[148:149], v[152:153]
	v_pk_mul_f32 v[152:153], v[166:167], v[164:165]
	v_pk_mul_f32 v[156:157], v[146:147], v[156:157]
	s_mov_b64 s[46:47], 0

; __device__ __forceinline__ float sigmoidf_(float x) { return __builtin_amdgcn_rcpf(1.f + __expf(-x)); }
;     __device__ __forceinline__ void operator()(const f32x4 (&acc)[2][2][4][2], const Unit& u, int wr, int wc, int fr, int fq) const {
;     ...
;             for (int ai = 0; ai < 2; ++ai)
; #pragma unroll
;                 for (int m = 0; m < 4; ++m) { const size_t off = (size_t)(row0 + ai * HALF + m * 16) * HW + c0;
;                     float o[8];
;                     if (ti & 1) {
; #pragma unroll
;                         for (int n = 0; n < 2; ++n)
; #pragma unroll
;                             for (int j = 0; j < 4; ++j) { const float g = acc[ai][1][m][n][j]; o[4 * n + j] = acc[ai][0][m][n][j] * g * sigmoidf_(g); }
;                     } else {
; #pragma unroll
;                         for (int n = 0; n < 2; ++n)
; #pragma unroll
;                             for (int j = 0; j < 4; ++j) o[4 * n + j] = acc[ai][0][m][n][j] * acc[ai][1][m][n][j];
;                     }
;                     u32x4 w; w.x = pkh(o[0], o[1]); w.y = pkh(o[2], o[3]); w.z = pkh(o[4], o[5]); w.w = pkh(o[6], o[7]);
;                     *(u32x4*)(dst + off) = w; }
.LBB0_129:
	v_lshlrev_b64 v[164:165], 12, v[142:143]
	v_cvt_pk_f16_f32 v147, v150, v151
	v_lshl_add_u64 v[150:151], v[144:145], 0, v[164:165]
	v_add_co_u32_e32 v150, vcc, 0x90000, v150
	v_cvt_pk_f16_f32 v146, v154, v155
	v_cvt_pk_f16_f32 v148, v156, v157
	v_cvt_pk_f16_f32 v149, v152, v153
	v_addc_co_u32_e32 v151, vcc, 0, v151, vcc
	global_store_dwordx4 v[150:151], v[146:149], off nt
	s_mov_b64 s[46:47], -1
	s_and_b64 vcc, exec, s[4:5]
	v_pk_mul_f32 v[148:149], v[36:37], v[12:13]
	v_pk_mul_f32 v[146:147], v[32:33], v[8:9]
	s_cbranch_vccnz .LBB0_131
	v_mul_f32_e32 v151, 0xbfb8aa3b, v13
	v_exp_f32_e32 v151, v151
	v_mul_f32_e32 v153, 0xbfb8aa3b, v15
	v_exp_f32_e32 v154, v153
	v_mul_f32_e32 v150, 0xbfb8aa3b, v12
	v_add_f32_e32 v151, 1.0, v151
	v_rcp_f32_e32 v153, v151
	v_add_f32_e32 v151, 1.0, v154
	v_mul_f32_e32 v154, 0xbfb8aa3b, v8
	v_exp_f32_e32 v154, v154
	v_mul_f32_e32 v155, 0xbfb8aa3b, v9
	v_exp_f32_e32 v150, v150
	v_exp_f32_e32 v155, v155
	v_add_f32_e32 v154, 1.0, v154
	v_rcp_f32_e32 v156, v154
	v_add_f32_e32 v150, 1.0, v150
	v_add_f32_e32 v154, 1.0, v155
	v_mul_f32_e32 v155, 0xbfb8aa3b, v10
	v_rcp_f32_e32 v152, v150
	v_mul_f32_e32 v150, 0xbfb8aa3b, v14
	v_exp_f32_e32 v155, v155
	v_mul_f32_e32 v157, 0xbfb8aa3b, v11
	v_exp_f32_e32 v150, v150
	v_exp_f32_e32 v165, v157
	v_rcp_f32_e32 v157, v154
	v_add_f32_e32 v154, 1.0, v155
	v_add_f32_e32 v150, 1.0, v150
	v_rcp_f32_e32 v164, v154
	v_add_f32_e32 v154, 1.0, v165
	v_rcp_f32_e32 v150, v150
	v_rcp_f32_e32 v151, v151
	v_rcp_f32_e32 v165, v154
	v_pk_mul_f32 v[154:155], v[38:39], v[14:15]
	v_pk_mul_f32 v[166:167], v[34:35], v[10:11]
	v_pk_mul_f32 v[150:151], v[154:155], v[150:151]
	v_pk_mul_f32 v[154:155], v[148:149], v[152:153]
	v_pk_mul_f32 v[152:153], v[166:167], v[164:165]
	v_pk_mul_f32 v[156:157], v[146:147], v[156:157]
	s_mov_b64 s[46:47], 0

; __device__ __forceinline__ float sigmoidf_(float x) { return __builtin_amdgcn_rcpf(1.f + __expf(-x)); }
;     __device__ __forceinline__ void operator()(const f32x4 (&acc)[2][2][4][2], const Unit& u, int wr, int wc, int fr, int fq) const {
;     ...
;             for (int ai = 0; ai < 2; ++ai)
; #pragma unroll
;                 for (int m = 0; m < 4; ++m) { const size_t off = (size_t)(row0 + ai * HALF + m * 16) * HW + c0;
;                     float o[8];
;                     if (ti & 1) {
; #pragma unroll
;                         for (int n = 0; n < 2; ++n)
; #pragma unroll
;                             for (int j = 0; j < 4; ++j) { const float g = acc[ai][1][m][n][j]; o[4 * n + j] = acc[ai][0][m][n][j] * g * sigmoidf_(g); }
;                     } else {
; #pragma unroll
;                         for (int n = 0; n < 2; ++n)
; #pragma unroll
;                             for (int j = 0; j < 4; ++j) o[4 * n + j] = acc[ai][0][m][n][j] * acc[ai][1][m][n][j];
;                     }
;                     u32x4 w; w.x = pkh(o[0], o[1]); w.y = pkh(o[2], o[3]); w.z = pkh(o[4], o[5]); w.w = pkh(o[6], o[7]);
;                     *(u32x4*)(dst + off) = w; }
.LBB0_133:
	v_lshlrev_b64 v[164:165], 12, v[142:143]
	v_cvt_pk_f16_f32 v147, v150, v151
	v_lshl_add_u64 v[150:151], v[144:145], 0, v[164:165]
	v_add_co_u32_e32 v150, vcc, 0xa0000, v150
	v_cvt_pk_f16_f32 v146, v154, v155
	v_cvt_pk_f16_f32 v148, v156, v157
	v_cvt_pk_f16_f32 v149, v152, v153
	v_addc_co_u32_e32 v151, vcc, 0, v151, vcc
	global_store_dwordx4 v[150:151], v[146:149], off nt
	s_mov_b64 s[46:47], -1
	s_and_b64 vcc, exec, s[4:5]
	v_pk_mul_f32 v[148:149], v[20:21], v[4:5]
	v_pk_mul_f32 v[146:147], v[16:17], v[0:1]
	s_cbranch_vccnz .LBB0_135
	v_mul_f32_e32 v151, 0xbfb8aa3b, v5
	v_exp_f32_e32 v151, v151
	v_mul_f32_e32 v153, 0xbfb8aa3b, v7
	v_exp_f32_e32 v154, v153
	v_mul_f32_e32 v150, 0xbfb8aa3b, v4
	v_add_f32_e32 v151, 1.0, v151
	v_rcp_f32_e32 v153, v151
	v_add_f32_e32 v151, 1.0, v154
	v_mul_f32_e32 v154, 0xbfb8aa3b, v0
	v_exp_f32_e32 v154, v154
	v_mul_f32_e32 v155, 0xbfb8aa3b, v1
	v_exp_f32_e32 v150, v150
	v_exp_f32_e32 v155, v155
	v_add_f32_e32 v154, 1.0, v154
	v_rcp_f32_e32 v156, v154
	v_add_f32_e32 v150, 1.0, v150
	v_add_f32_e32 v154, 1.0, v155
	v_mul_f32_e32 v155, 0xbfb8aa3b, v2
	v_rcp_f32_e32 v152, v150
	v_mul_f32_e32 v150, 0xbfb8aa3b, v6
	v_exp_f32_e32 v155, v155
	v_mul_f32_e32 v157, 0xbfb8aa3b, v3
	v_exp_f32_e32 v150, v150
	v_exp_f32_e32 v165, v157
	v_rcp_f32_e32 v157, v154
	v_add_f32_e32 v154, 1.0, v155
	v_add_f32_e32 v150, 1.0, v150
	v_rcp_f32_e32 v164, v154
	v_add_f32_e32 v154, 1.0, v165
	v_rcp_f32_e32 v150, v150
	v_rcp_f32_e32 v151, v151
	v_rcp_f32_e32 v165, v154
	v_pk_mul_f32 v[154:155], v[22:23], v[6:7]
	v_pk_mul_f32 v[166:167], v[18:19], v[2:3]
	v_pk_mul_f32 v[150:151], v[154:155], v[150:151]
	v_pk_mul_f32 v[154:155], v[148:149], v[152:153]
	v_pk_mul_f32 v[152:153], v[166:167], v[164:165]
	v_pk_mul_f32 v[156:157], v[146:147], v[156:157]
	s_mov_b64 s[46:47], 0

; __device__ __forceinline__ float sigmoidf_(float x) { return __builtin_amdgcn_rcpf(1.f + __expf(-x)); }
;     __device__ __forceinline__ void operator()(const f32x4 (&acc)[2][2][4][2], const Unit& u, int wr, int wc, int fr, int fq) const {
;     ...
;             for (int ai = 0; ai < 2; ++ai)
; #pragma unroll
;                 for (int m = 0; m < 4; ++m) { const size_t off = (size_t)(row0 + ai * HALF + m * 16) * HW + c0;
;                     float o[8];
;                     if (ti & 1) {
; #pragma unroll
;                         for (int n = 0; n < 2; ++n)
; #pragma unroll
;                             for (int j = 0; j < 4; ++j) { const float g = acc[ai][1][m][n][j]; o[4 * n + j] = acc[ai][0][m][n][j] * g * sigmoidf_(g); }
;                     } else {
; #pragma unroll
;                         for (int n = 0; n < 2; ++n)
; #pragma unroll
;                             for (int j = 0; j < 4; ++j) o[4 * n + j] = acc[ai][0][m][n][j] * acc[ai][1][m][n][j];
;                     }
;                     u32x4 w; w.x = pkh(o[0], o[1]); w.y = pkh(o[2], o[3]); w.z = pkh(o[4], o[5]); w.w = pkh(o[6], o[7]);
;                     *(u32x4*)(dst + off) = w; }
.LBB0_137:
	v_lshlrev_b64 v[164:165], 12, v[142:143]
	v_lshl_add_u64 v[144:145], v[144:145], 0, v[164:165]
	v_add_co_u32_e32 v144, vcc, 0xb0000, v144
	v_cvt_pk_f16_f32 v146, v154, v155
	v_cvt_pk_f16_f32 v147, v150, v151
	v_cvt_pk_f16_f32 v148, v156, v157
	v_cvt_pk_f16_f32 v149, v152, v153
	v_addc_co_u32_e32 v145, vcc, 0, v145, vcc
	global_store_dwordx4 v[144:145], v[146:149], off nt

;     __device__ __forceinline__ void operator()(const f32x4 (&acc)[2][2][4][2], const Unit& u, int wr, int wc, int fr, int fq) const {
;     ...
;         if ((u.pn & 1) == 0) {
;             h16* base = PA + 256 * (u.pn >> 1) + wc * 32 + 8 * fq;
; #pragma unroll
;             for (int ai = 0; ai < 2; ++ai)
; #pragma unroll
;                 for (int m = 0; m < 4; ++m) { h16* rowp = base + (size_t)(row0 + ai * HALF + m * 16) * 8192;
; #pragma unroll
;                     for (int bj = 0; bj < 2; ++bj) { const f32x4 v0 = acc[ai][bj][m][0], v1 = acc[ai][bj][m][1];
;                         u32x4 w; w.x = pkh(v0[0], v0[1]); w.y = pkh(v0[2], v0[3]); w.z = pkh(v1[0], v1[1]); w.w = pkh(v1[2], v1[3]);
;                         *(u32x4*)(rowp + bj * HALF) = w; } }
.LBB0_139:
	s_and_b64 vcc, exec, s[4:5]
	s_cbranch_vccz .LBB0_138
	s_lshl_b32 s4, s18, 7
	s_ashr_i32 s5, s4, 31
	v_ashrrev_i32_e32 v143, 31, v142
	v_lshl_add_u64 v[144:145], s[4:5], 1, v[132:133]
	v_lshlrev_b64 v[146:147], 14, v[142:143]
	v_lshl_add_u64 v[146:147], v[144:145], 0, v[146:147]
	v_cvt_pk_f16_f32 v60, v60, v61
	v_cvt_pk_f16_f32 v61, v62, v63
	v_cvt_pk_f16_f32 v62, v56, v57
	v_add_co_u32_e32 v56, vcc, s71, v146
	v_cvt_pk_f16_f32 v68, v68, v69
	v_cvt_pk_f16_f32 v69, v70, v71
	v_cvt_pk_f16_f32 v70, v64, v65
	v_lshl_add_u64 v[64:65], v[146:147], 0, s[10:11]
	v_addc_co_u32_e32 v57, vcc, 0, v147, vcc
	v_cvt_pk_f16_f32 v44, v44, v45
	v_cvt_pk_f16_f32 v45, v46, v47
	v_cvt_pk_f16_f32 v46, v40, v41
	v_cvt_pk_f16_f32 v47, v42, v43
	v_cvt_pk_f16_f32 v108, v108, v109
	v_cvt_pk_f16_f32 v109, v110, v111
	v_cvt_pk_f16_f32 v110, v104, v105
	v_or_b32_e32 v104, 16, v142
	global_store_dwordx4 v[64:65], v[44:47], off offset:256 nt
	v_ashrrev_i32_e32 v105, 31, v104
	v_cvt_pk_f16_f32 v92, v92, v93
	v_add_co_u32_e32 v46, vcc, s72, v146
	v_cvt_pk_f16_f32 v93, v94, v95
	v_cvt_pk_f16_f32 v94, v88, v89
	v_or_b32_e32 v88, 32, v142
	v_lshl_add_u64 v[44:45], v[146:147], 0, s[20:21]
	v_addc_co_u32_e32 v47, vcc, 0, v147, vcc
	v_cvt_pk_f16_f32 v28, v28, v29
	v_cvt_pk_f16_f32 v29, v30, v31
	v_cvt_pk_f16_f32 v30, v24, v25
	v_cvt_pk_f16_f32 v31, v26, v27
	v_cvt_pk_f16_f32 v111, v106, v107
	v_lshlrev_b64 v[104:105], 14, v[104:105]
	v_ashrrev_i32_e32 v89, 31, v88
	v_cvt_pk_f16_f32 v76, v76, v77
	v_cvt_pk_f16_f32 v77, v78, v79
	v_cvt_pk_f16_f32 v78, v72, v73
	v_or_b32_e32 v72, 48, v142
	global_store_dwordx4 v[44:45], v[28:31], off offset:256 nt
	global_store_dwordx4 v[146:147], v[108:111], off offset:256 nt
	v_cvt_pk_f16_f32 v95, v90, v91
	v_add_co_u32_e32 v30, vcc, s73, v146
	v_lshl_add_u64 v[108:109], v[144:145], 0, v[104:105]
	v_lshlrev_b64 v[88:89], 14, v[88:89]
	v_ashrrev_i32_e32 v73, 31, v72
	v_lshl_add_u64 v[28:29], v[146:147], 0, s[22:23]
	v_addc_co_u32_e32 v31, vcc, 0, v147, vcc
	v_cvt_pk_f16_f32 v12, v12, v13
	v_cvt_pk_f16_f32 v13, v14, v15
	v_cvt_pk_f16_f32 v14, v8, v9
	v_cvt_pk_f16_f32 v15, v10, v11
	global_store_dwordx4 v[108:109], v[92:95], off offset:256 nt
	v_cvt_pk_f16_f32 v79, v74, v75
	v_lshlrev_b64 v[72:73], 14, v[72:73]
	v_lshl_add_u64 v[92:93], v[144:145], 0, v[88:89]
	global_store_dwordx4 v[28:29], v[12:15], off offset:256 nt
	v_cvt_pk_f16_f32 v124, v124, v125
	v_cvt_pk_f16_f32 v125, v126, v127
	v_add_co_u32_e32 v14, vcc, 0x2c0000, v146
	v_cvt_pk_f16_f32 v126, v120, v121
	v_cvt_pk_f16_f32 v127, v122, v123
	v_cvt_pk_f16_f32 v104, v116, v117
	v_cvt_pk_f16_f32 v105, v118, v119
	v_cvt_pk_f16_f32 v106, v112, v113
	v_cvt_pk_f16_f32 v107, v114, v115
	v_cvt_pk_f16_f32 v88, v100, v101
	v_cvt_pk_f16_f32 v89, v102, v103
	v_cvt_pk_f16_f32 v90, v96, v97
	v_cvt_pk_f16_f32 v91, v98, v99
	global_store_dwordx4 v[92:93], v[76:79], off offset:256 nt
	v_cvt_pk_f16_f32 v74, v80, v81
	v_cvt_pk_f16_f32 v75, v82, v83
	v_lshl_add_u64 v[76:77], v[144:145], 0, v[72:73]
	v_cvt_pk_f16_f32 v72, v84, v85
	v_cvt_pk_f16_f32 v73, v86, v87
	v_cvt_pk_f16_f32 v71, v66, v67
	v_cvt_pk_f16_f32 v63, v58, v59
	v_cvt_pk_f16_f32 v40, v52, v53
	v_cvt_pk_f16_f32 v41, v54, v55
	v_cvt_pk_f16_f32 v42, v48, v49
	v_cvt_pk_f16_f32 v43, v50, v51
	v_cvt_pk_f16_f32 v24, v36, v37
	v_cvt_pk_f16_f32 v25, v38, v39
	v_cvt_pk_f16_f32 v26, v32, v33
	v_cvt_pk_f16_f32 v27, v34, v35
	v_lshl_add_u64 v[12:13], v[146:147], 0, s[24:25]
	v_cvt_pk_f16_f32 v8, v20, v21
	v_cvt_pk_f16_f32 v9, v22, v23
	v_cvt_pk_f16_f32 v10, v16, v17
	v_cvt_pk_f16_f32 v11, v18, v19
	v_addc_co_u32_e32 v15, vcc, 0, v147, vcc
	v_cvt_pk_f16_f32 v4, v4, v5
	v_cvt_pk_f16_f32 v5, v6, v7
	v_cvt_pk_f16_f32 v6, v0, v1
	v_cvt_pk_f16_f32 v7, v2, v3
	global_store_dwordx4 v[146:147], v[124:127], off nt
	global_store_dwordx4 v[108:109], v[104:107], off nt
	global_store_dwordx4 v[92:93], v[88:91], off nt
	global_store_dwordx4 v[76:77], v[72:75], off nt
	global_store_dwordx4 v[76:77], v[68:71], off offset:256 nt
	global_store_dwordx4 v[56:57], v[60:63], off nt
	global_store_dwordx4 v[46:47], v[40:43], off nt
	global_store_dwordx4 v[30:31], v[24:27], off nt
	global_store_dwordx4 v[14:15], v[8:11], off nt
	global_store_dwordx4 v[12:13], v[4:7], off offset:256 nt
	s_andn2_b64 vcc, exec, s[0:1]
	s_mov_b64 s[0:1], -1
	s_cbranch_vccnz .LBB0_93

;     __device__ __forceinline__ void operator()(const f32x4 (&acc)[2][2][4][2], const Unit& u, int wr, int wc, int fr, int fq) const {
;         const int row0 = u.pm * BM + wr * 64 + fr;
;         const int c0 = u.pn * 128 + 32 * wc + 8 * fq;
;         constexpr float DS = 1.f / (F8_SU * F8_SW);
;         f32x4 ba[2], bb[2];
; #pragma unroll
;         for (int n = 0; n < 2; ++n) { ba[n] = *(const f32x4*)(gbias + c0 + 4 * n); bb[n] = *(const f32x4*)(gbias + D + c0 + 4 * n); }
; #pragma unroll
;         for (int ai = 0; ai < 2; ++ai)
; #pragma unroll
;             for (int m = 0; m < 4; ++m) {
;                 h16* rowp = PG + (size_t)(u.pm * 32 + u.pn) * 65536 + (ai * 4 + m) * 4096 + (wr * 4 + wc) * 512 + (fq * 16 + fr) * 8;
;                 float r[8], sg[8];
; #pragma unroll
;                 for (int n = 0; n < 2; ++n)
; #pragma unroll
;                     for (int j = 0; j < 4; ++j) { const float ea = __expf(-(acc[ai][0][m][n][j] * DS + ba[n][j])), eb = __expf(-(acc[ai][1][m][n][j] * DS + bb[n][j]));
;                         const float pa = 1.f + ea, pb = 1.f + eb, rp = __builtin_amdgcn_rcpf(pa * pb);
;                         sg[4 * n + j] = pa * rp; r[4 * n + j] = pb * pb * rp; }
;                 u32x4 w; w.x = pkh(r[0], r[1]); w.y = pkh(r[2], r[3]); w.z = pkh(r[4], r[5]); w.w = pkh(r[6], r[7]);
;                 *(u32x4*)rowp = w;
;                 w.x = pkh(sg[0], sg[1]); w.y = pkh(sg[2], sg[3]); w.z = pkh(sg[4], sg[5]); w.w = pkh(sg[6], sg[7]);
;                 *(u32x4*)(rowp + 32768) = w; }
.LBB0_160:
	v_lshl_or_b32 v0, s27, 7, v183
	v_ashrrev_i32_e32 v1, 31, v0
	v_lshlrev_b64 v[0:1], 2, v[0:1]
	s_nop 15
	s_nop 15
	v_lshl_add_u64 v[2:3], s[8:9], 0, v[0:1]
	v_lshl_add_u64 v[0:1], s[14:15], 0, v[0:1]
	global_load_dwordx4 v[12:15], v[2:3], off
	global_load_dwordx4 v[8:11], v[0:1], off
	global_load_dwordx4 v[4:7], v[2:3], off offset:16
	s_nop 0
	global_load_dwordx4 v[0:3], v[0:1], off offset:16
	s_lshl_b32 s19, s26, 5
	s_add_i32 s26, s19, s27
	s_ashr_i32 s27, s26, 31
	s_lshl_b64 s[26:27], s[26:27], 17
	s_add_u32 s19, s53, s26
	s_addc_u32 s21, s7, s27
	s_add_u32 s26, s19, s16
	s_addc_u32 s27, s21, s17
	v_lshl_add_u64 v[16:17], s[26:27], 0, v[164:165]
	s_waitcnt vmcnt(0)
	v_fmamk_f32 v18, v156, 0x3a000000, v12
	v_fmamk_f32 v19, v148, 0x3a000000, v8
	v_fmamk_f32 v20, v157, 0x3a000000, v13
	v_fmamk_f32 v21, v149, 0x3a000000, v9
	v_fmamk_f32 v22, v158, 0x3a000000, v14
	v_fmamk_f32 v23, v150, 0x3a000000, v10
	v_fmamk_f32 v24, v159, 0x3a000000, v15
	v_fmamk_f32 v25, v151, 0x3a000000, v11
	v_fmamk_f32 v26, v152, 0x3a000000, v4
	v_fmamk_f32 v27, v144, 0x3a000000, v0
	v_fmamk_f32 v28, v153, 0x3a000000, v5
	v_fmamk_f32 v29, v145, 0x3a000000, v1
	v_fmamk_f32 v30, v154, 0x3a000000, v6
	v_fmamk_f32 v31, v146, 0x3a000000, v2
	v_fmamk_f32 v144, v155, 0x3a000000, v7
	v_fmamk_f32 v145, v147, 0x3a000000, v3
	v_mul_f32_e32 v18, 0xbfb8aa3b, v18
	v_mul_f32_e32 v19, 0xbfb8aa3b, v19
	v_mul_f32_e32 v146, 0xbfb8aa3b, v20
	v_mul_f32_e32 v21, 0xbfb8aa3b, v21
	v_mul_f32_e32 v22, 0xbfb8aa3b, v22
	v_mul_f32_e32 v23, 0xbfb8aa3b, v23
	v_mul_f32_e32 v147, 0xbfb8aa3b, v24
	v_mul_f32_e32 v25, 0xbfb8aa3b, v25
	v_mul_f32_e32 v26, 0xbfb8aa3b, v26
	v_mul_f32_e32 v27, 0xbfb8aa3b, v27
	v_mul_f32_e32 v148, 0xbfb8aa3b, v28
	v_mul_f32_e32 v29, 0xbfb8aa3b, v29
	v_mul_f32_e32 v30, 0xbfb8aa3b, v30
	v_mul_f32_e32 v31, 0xbfb8aa3b, v31
	v_mul_f32_e32 v149, 0xbfb8aa3b, v144
	v_mul_f32_e32 v145, 0xbfb8aa3b, v145
	v_exp_f32_e32 v18, v18
	v_exp_f32_e32 v20, v19
	v_exp_f32_e32 v19, v146
	v_exp_f32_e32 v21, v21
	v_exp_f32_e32 v22, v22
	v_exp_f32_e32 v24, v23
	v_exp_f32_e32 v23, v147
	v_exp_f32_e32 v25, v25
	v_exp_f32_e32 v26, v26
	v_exp_f32_e32 v28, v27
	v_exp_f32_e32 v27, v148
	v_exp_f32_e32 v29, v29
	v_exp_f32_e32 v30, v30
	v_exp_f32_e32 v144, v31
	v_exp_f32_e32 v31, v149
	v_exp_f32_e32 v145, v145
	v_pk_add_f32 v[20:21], v[20:21], 1.0 op_sel_hi:[1,0]
	v_pk_add_f32 v[24:25], v[24:25], 1.0 op_sel_hi:[1,0]
	v_pk_add_f32 v[18:19], v[18:19], 1.0 op_sel_hi:[1,0]
	v_pk_add_f32 v[22:23], v[22:23], 1.0 op_sel_hi:[1,0]
	v_pk_add_f32 v[28:29], v[28:29], 1.0 op_sel_hi:[1,0]
	v_pk_add_f32 v[144:145], v[144:145], 1.0 op_sel_hi:[1,0]
	v_pk_add_f32 v[26:27], v[26:27], 1.0 op_sel_hi:[1,0]
	v_pk_add_f32 v[30:31], v[30:31], 1.0 op_sel_hi:[1,0]
	v_pk_mul_f32 v[146:147], v[20:21], v[20:21]
	v_pk_mul_f32 v[148:149], v[24:25], v[24:25]
	v_pk_mul_f32 v[20:21], v[18:19], v[20:21]
	v_pk_mul_f32 v[24:25], v[22:23], v[24:25]
	v_pk_mul_f32 v[150:151], v[28:29], v[28:29]
	v_pk_mul_f32 v[152:153], v[144:145], v[144:145]
	v_pk_mul_f32 v[28:29], v[26:27], v[28:29]
	v_pk_mul_f32 v[144:145], v[30:31], v[144:145]
	v_rcp_f32_e32 v20, v20
	v_rcp_f32_e32 v21, v21
	v_rcp_f32_e32 v24, v24
	v_rcp_f32_e32 v25, v25
	v_rcp_f32_e32 v28, v28
	v_rcp_f32_e32 v29, v29
	v_rcp_f32_e32 v144, v144
	v_rcp_f32_e32 v145, v145
	v_pk_mul_f32 v[154:155], v[18:19], v[20:21]
	v_pk_mul_f32 v[18:19], v[146:147], v[20:21]
	v_pk_mul_f32 v[20:21], v[22:23], v[24:25]
	v_pk_mul_f32 v[24:25], v[148:149], v[24:25]
	v_pk_mul_f32 v[26:27], v[26:27], v[28:29]
	v_cvt_pk_f16_f32 v23, v20, v21
	v_pk_mul_f32 v[20:21], v[150:151], v[28:29]
	v_pk_mul_f32 v[28:29], v[152:153], v[144:145]
	v_cvt_pk_f16_f32 v18, v18, v19
	v_cvt_pk_f16_f32 v19, v24, v25
	v_cvt_pk_f16_f32 v20, v20, v21
	v_cvt_pk_f16_f32 v21, v28, v29
	v_cvt_pk_f16_f32 v24, v26, v27
	v_pk_mul_f32 v[26:27], v[30:31], v[144:145]
	global_store_dwordx4 v164, v[18:21], s[26:27] nt
	v_cvt_pk_f16_f32 v22, v154, v155
	v_cvt_pk_f16_f32 v25, v26, v27
	v_add_co_u32_e32 v18, vcc, s59, v16
	v_fmamk_f32 v21, v133, 0x3a000000, v9
	s_nop 0
	v_addc_co_u32_e32 v19, vcc, 0, v17, vcc
	global_store_dwordx4 v[18:19], v[22:25], off nt
	v_fmamk_f32 v19, v132, 0x3a000000, v8
	v_mul_f32_e32 v19, 0xbfb8aa3b, v19
	v_fmamk_f32 v18, v140, 0x3a000000, v12
	v_exp_f32_e32 v20, v19
	v_fmamk_f32 v19, v141, 0x3a000000, v13
	v_mul_f32_e32 v18, 0xbfb8aa3b, v18
	v_mul_f32_e32 v19, 0xbfb8aa3b, v19
	v_mul_f32_e32 v21, 0xbfb8aa3b, v21
	v_exp_f32_e32 v18, v18
	v_exp_f32_e32 v19, v19
	v_exp_f32_e32 v21, v21
	v_fmamk_f32 v23, v134, 0x3a000000, v10
	v_mul_f32_e32 v23, 0xbfb8aa3b, v23
	v_fmamk_f32 v27, v128, 0x3a000000, v0
	v_fmamk_f32 v22, v142, 0x3a000000, v14
	v_exp_f32_e32 v24, v23
	v_fmamk_f32 v23, v143, 0x3a000000, v15
	v_fmamk_f32 v25, v135, 0x3a000000, v11
	v_mul_f32_e32 v27, 0xbfb8aa3b, v27
	v_mul_f32_e32 v22, 0xbfb8aa3b, v22
	v_mul_f32_e32 v23, 0xbfb8aa3b, v23
	v_mul_f32_e32 v25, 0xbfb8aa3b, v25
	v_fmamk_f32 v26, v136, 0x3a000000, v4
	v_exp_f32_e32 v28, v27
	v_fmamk_f32 v27, v137, 0x3a000000, v5
	v_fmamk_f32 v29, v129, 0x3a000000, v1
	v_pk_add_f32 v[20:21], v[20:21], 1.0 op_sel_hi:[1,0]
	v_pk_add_f32 v[18:19], v[18:19], 1.0 op_sel_hi:[1,0]
	v_exp_f32_e32 v22, v22
	v_exp_f32_e32 v23, v23
	v_exp_f32_e32 v25, v25
	v_mul_f32_e32 v26, 0xbfb8aa3b, v26
	v_mul_f32_e32 v27, 0xbfb8aa3b, v27
	v_mul_f32_e32 v29, 0xbfb8aa3b, v29
	v_fmamk_f32 v31, v130, 0x3a000000, v2
	v_fmamk_f32 v129, v131, 0x3a000000, v3
	v_pk_mul_f32 v[130:131], v[20:21], v[20:21]
	v_pk_mul_f32 v[20:21], v[18:19], v[20:21]
	v_exp_f32_e32 v26, v26
	v_exp_f32_e32 v27, v27
	v_exp_f32_e32 v29, v29
	v_rcp_f32_e32 v20, v20
	v_rcp_f32_e32 v21, v21
	v_mul_f32_e32 v31, 0xbfb8aa3b, v31
;     __device__ __forceinline__ void operator()(const f32x4 (&acc)[2][2][4][2], const Unit& u, int wr, int wc, int fr, int fq) const {
;         const int row0 = u.pm * BM + wr * 64 + fr;
;         const int c0 = u.pn * 128 + 32 * wc + 8 * fq;
;         constexpr float DS = 1.f / (F8_SU * F8_SW);
;         f32x4 ba[2], bb[2];
; #pragma unroll
;         for (int n = 0; n < 2; ++n) { ba[n] = *(const f32x4*)(gbias + c0 + 4 * n); bb[n] = *(const f32x4*)(gbias + D + c0 + 4 * n); }
; #pragma unroll
;         for (int ai = 0; ai < 2; ++ai)
; #pragma unroll
;             for (int m = 0; m < 4; ++m) {
;                 h16* rowp = PG + (size_t)(u.pm * 32 + u.pn) * 65536 + (ai * 4 + m) * 4096 + (wr * 4 + wc) * 512 + (fq * 16 + fr) * 8;
;                 float r[8], sg[8];
; #pragma unroll
;                 for (int n = 0; n < 2; ++n)
; #pragma unroll
;                     for (int j = 0; j < 4; ++j) { const float ea = __expf(-(acc[ai][0][m][n][j] * DS + ba[n][j])), eb = __expf(-(acc[ai][1][m][n][j] * DS + bb[n][j]));
;                         const float pa = 1.f + ea, pb = 1.f + eb, rp = __builtin_amdgcn_rcpf(pa * pb);
;                         sg[4 * n + j] = pa * rp; r[4 * n + j] = pb * pb * rp; }
;                 u32x4 w; w.x = pkh(r[0], r[1]); w.y = pkh(r[2], r[3]); w.z = pkh(r[4], r[5]); w.w = pkh(r[6], r[7]);
;                 *(u32x4*)rowp = w;
;                 w.x = pkh(sg[0], sg[1]); w.y = pkh(sg[2], sg[3]); w.z = pkh(sg[4], sg[5]); w.w = pkh(sg[6], sg[7]);
;                 *(u32x4*)(rowp + 32768) = w; }
	v_pk_add_f32 v[24:25], v[24:25], 1.0 op_sel_hi:[1,0]
	v_pk_add_f32 v[140:141], v[22:23], 1.0 op_sel_hi:[1,0]
	v_fmamk_f32 v30, v138, 0x3a000000, v6
	v_exp_f32_e32 v128, v31
	v_fmamk_f32 v31, v139, 0x3a000000, v7
	v_pk_add_f32 v[28:29], v[28:29], 1.0 op_sel_hi:[1,0]
	v_pk_mul_f32 v[138:139], v[18:19], v[20:21]
	v_pk_mul_f32 v[18:19], v[140:141], v[24:25]
	v_pk_add_f32 v[26:27], v[26:27], 1.0 op_sel_hi:[1,0]
	v_mul_f32_e32 v30, 0xbfb8aa3b, v30
	v_mul_f32_e32 v31, 0xbfb8aa3b, v31
	v_mul_f32_e32 v129, 0xbfb8aa3b, v129
	v_pk_mul_f32 v[132:133], v[24:25], v[24:25]
	v_pk_mul_f32 v[134:135], v[28:29], v[28:29]
	v_rcp_f32_e32 v24, v18
	v_rcp_f32_e32 v25, v19
	v_pk_mul_f32 v[28:29], v[26:27], v[28:29]
	v_exp_f32_e32 v30, v30
	v_exp_f32_e32 v31, v31
	v_exp_f32_e32 v129, v129
	v_rcp_f32_e32 v28, v28
	v_rcp_f32_e32 v29, v29
	v_pk_mul_f32 v[18:19], v[130:131], v[20:21]
	v_pk_mul_f32 v[20:21], v[140:141], v[24:25]
	v_pk_mul_f32 v[24:25], v[132:133], v[24:25]
	v_pk_add_f32 v[128:129], v[128:129], 1.0 op_sel_hi:[1,0]
	v_cvt_pk_f16_f32 v18, v18, v19
	v_cvt_pk_f16_f32 v19, v24, v25
	v_pk_mul_f32 v[24:25], v[26:27], v[28:29]
	v_pk_add_f32 v[26:27], v[30:31], 1.0 op_sel_hi:[1,0]
	v_cvt_pk_f16_f32 v23, v20, v21
	v_pk_mul_f32 v[20:21], v[26:27], v[128:129]
	v_pk_mul_f32 v[136:137], v[128:129], v[128:129]
	v_rcp_f32_e32 v30, v20
	v_rcp_f32_e32 v31, v21
	v_pk_mul_f32 v[20:21], v[134:135], v[28:29]
	v_cvt_pk_f16_f32 v22, v138, v139
	v_cvt_pk_f16_f32 v20, v20, v21
	v_pk_mul_f32 v[28:29], v[136:137], v[30:31]
	v_pk_mul_f32 v[26:27], v[26:27], v[30:31]
	v_cvt_pk_f16_f32 v21, v28, v29
	v_add_co_u32_e32 v28, vcc, s57, v16
	v_cvt_pk_f16_f32 v24, v24, v25
	s_nop 0
	v_addc_co_u32_e32 v29, vcc, 0, v17, vcc
	global_store_dwordx4 v[28:29], v[18:21], off nt
	v_cvt_pk_f16_f32 v25, v26, v27
	v_fmamk_f32 v27, v112, 0x3a000000, v0
	v_add_co_u32_e32 v18, vcc, s60, v16
	v_fmamk_f32 v21, v117, 0x3a000000, v9
	s_nop 0
	v_addc_co_u32_e32 v19, vcc, 0, v17, vcc
	global_store_dwordx4 v[18:19], v[22:25], off nt
	v_fmamk_f32 v19, v116, 0x3a000000, v8
	v_mul_f32_e32 v19, 0xbfb8aa3b, v19
	v_fmamk_f32 v18, v124, 0x3a000000, v12
	v_exp_f32_e32 v20, v19
	v_fmamk_f32 v19, v125, 0x3a000000, v13
	v_mul_f32_e32 v18, 0xbfb8aa3b, v18
	v_mul_f32_e32 v19, 0xbfb8aa3b, v19
	v_mul_f32_e32 v21, 0xbfb8aa3b, v21
	v_exp_f32_e32 v18, v18
	v_exp_f32_e32 v19, v19
	v_exp_f32_e32 v21, v21
	v_fmamk_f32 v23, v118, 0x3a000000, v10
	v_mul_f32_e32 v23, 0xbfb8aa3b, v23
	v_fmamk_f32 v22, v126, 0x3a000000, v14
	v_exp_f32_e32 v24, v23
	v_fmamk_f32 v23, v127, 0x3a000000, v15
	v_fmamk_f32 v25, v119, 0x3a000000, v11
	v_mul_f32_e32 v27, 0xbfb8aa3b, v27
	v_mul_f32_e32 v22, 0xbfb8aa3b, v22
	v_mul_f32_e32 v23, 0xbfb8aa3b, v23
	v_mul_f32_e32 v25, 0xbfb8aa3b, v25
	v_fmamk_f32 v26, v120, 0x3a000000, v4
	v_exp_f32_e32 v28, v27
	v_fmamk_f32 v27, v121, 0x3a000000, v5
	v_fmamk_f32 v29, v113, 0x3a000000, v1
	v_pk_add_f32 v[20:21], v[20:21], 1.0 op_sel_hi:[1,0]
	v_pk_add_f32 v[18:19], v[18:19], 1.0 op_sel_hi:[1,0]
	v_exp_f32_e32 v22, v22
	v_exp_f32_e32 v23, v23
	v_exp_f32_e32 v25, v25
	v_mul_f32_e32 v26, 0xbfb8aa3b, v26
	v_mul_f32_e32 v27, 0xbfb8aa3b, v27
	v_mul_f32_e32 v29, 0xbfb8aa3b, v29
	v_fmamk_f32 v31, v114, 0x3a000000, v2
	v_fmamk_f32 v113, v115, 0x3a000000, v3
	v_pk_mul_f32 v[114:115], v[20:21], v[20:21]
	v_pk_mul_f32 v[20:21], v[18:19], v[20:21]
	v_exp_f32_e32 v26, v26
	v_exp_f32_e32 v27, v27
	v_exp_f32_e32 v29, v29
	v_rcp_f32_e32 v20, v20
	v_rcp_f32_e32 v21, v21
	v_mul_f32_e32 v31, 0xbfb8aa3b, v31
	v_pk_add_f32 v[24:25], v[24:25], 1.0 op_sel_hi:[1,0]
	v_pk_add_f32 v[124:125], v[22:23], 1.0 op_sel_hi:[1,0]
	v_fmamk_f32 v30, v122, 0x3a000000, v6
	v_exp_f32_e32 v112, v31
	v_fmamk_f32 v31, v123, 0x3a000000, v7
	v_pk_add_f32 v[28:29], v[28:29], 1.0 op_sel_hi:[1,0]
	v_pk_mul_f32 v[122:123], v[18:19], v[20:21]
	v_pk_mul_f32 v[18:19], v[124:125], v[24:25]
	v_pk_add_f32 v[26:27], v[26:27], 1.0 op_sel_hi:[1,0]
	v_mul_f32_e32 v30, 0xbfb8aa3b, v30
	v_mul_f32_e32 v31, 0xbfb8aa3b, v31
	v_mul_f32_e32 v113, 0xbfb8aa3b, v113
	v_pk_mul_f32 v[116:117], v[24:25], v[24:25]
	v_pk_mul_f32 v[118:119], v[28:29], v[28:29]
	v_rcp_f32_e32 v24, v18
	v_rcp_f32_e32 v25, v19
	v_pk_mul_f32 v[28:29], v[26:27], v[28:29]
	v_exp_f32_e32 v30, v30
	v_exp_f32_e32 v31, v31
	v_exp_f32_e32 v113, v113
	v_rcp_f32_e32 v28, v28
	v_rcp_f32_e32 v29, v29
	v_pk_mul_f32 v[18:19], v[114:115], v[20:21]
	v_pk_mul_f32 v[20:21], v[124:125], v[24:25]
	v_pk_mul_f32 v[24:25], v[116:117], v[24:25]
	v_pk_add_f32 v[112:113], v[112:113], 1.0 op_sel_hi:[1,0]
	v_cvt_pk_f16_f32 v18, v18, v19
	v_cvt_pk_f16_f32 v19, v24, v25
	v_pk_mul_f32 v[24:25], v[26:27], v[28:29]
	v_pk_add_f32 v[26:27], v[30:31], 1.0 op_sel_hi:[1,0]
	v_cvt_pk_f16_f32 v23, v20, v21
	v_pk_mul_f32 v[20:21], v[26:27], v[112:113]
	v_pk_mul_f32 v[120:121], v[112:113], v[112:113]
	v_rcp_f32_e32 v30, v20
	v_rcp_f32_e32 v31, v21
	v_pk_mul_f32 v[20:21], v[118:119], v[28:29]
	v_cvt_pk_f16_f32 v22, v122, v123
	v_cvt_pk_f16_f32 v20, v20, v21
	v_pk_mul_f32 v[28:29], v[120:121], v[30:31]
	v_pk_mul_f32 v[26:27], v[26:27], v[30:31]
	v_cvt_pk_f16_f32 v21, v28, v29
	v_add_co_u32_e32 v28, vcc, s63, v16
	v_cvt_pk_f16_f32 v24, v24, v25
	s_nop 0
	v_addc_co_u32_e32 v29, vcc, 0, v17, vcc
	global_store_dwordx4 v[28:29], v[18:21], off nt
	v_cvt_pk_f16_f32 v25, v26, v27
	v_fmamk_f32 v27, v96, 0x3a000000, v0
	v_add_co_u32_e32 v18, vcc, s61, v16
	v_fmamk_f32 v21, v101, 0x3a000000, v9
	s_nop 0
	v_addc_co_u32_e32 v19, vcc, 0, v17, vcc
	global_store_dwordx4 v[18:19], v[22:25], off nt
	v_fmamk_f32 v19, v100, 0x3a000000, v8
	v_mul_f32_e32 v19, 0xbfb8aa3b, v19
	v_fmamk_f32 v18, v108, 0x3a000000, v12
	v_exp_f32_e32 v20, v19
	v_fmamk_f32 v19, v109, 0x3a000000, v13
;     __device__ __forceinline__ void operator()(const f32x4 (&acc)[2][2][4][2], const Unit& u, int wr, int wc, int fr, int fq) const {
;         const int row0 = u.pm * BM + wr * 64 + fr;
;         const int c0 = u.pn * 128 + 32 * wc + 8 * fq;
;         constexpr float DS = 1.f / (F8_SU * F8_SW);
;         f32x4 ba[2], bb[2];
; #pragma unroll
;         for (int n = 0; n < 2; ++n) { ba[n] = *(const f32x4*)(gbias + c0 + 4 * n); bb[n] = *(const f32x4*)(gbias + D + c0 + 4 * n); }
; #pragma unroll
;         for (int ai = 0; ai < 2; ++ai)
; #pragma unroll
;             for (int m = 0; m < 4; ++m) {
;                 h16* rowp = PG + (size_t)(u.pm * 32 + u.pn) * 65536 + (ai * 4 + m) * 4096 + (wr * 4 + wc) * 512 + (fq * 16 + fr) * 8;
;                 float r[8], sg[8];
; #pragma unroll
;                 for (int n = 0; n < 2; ++n)
; #pragma unroll
;                     for (int j = 0; j < 4; ++j) { const float ea = __expf(-(acc[ai][0][m][n][j] * DS + ba[n][j])), eb = __expf(-(acc[ai][1][m][n][j] * DS + bb[n][j]));
;                         const float pa = 1.f + ea, pb = 1.f + eb, rp = __builtin_amdgcn_rcpf(pa * pb);
;                         sg[4 * n + j] = pa * rp; r[4 * n + j] = pb * pb * rp; }
;                 u32x4 w; w.x = pkh(r[0], r[1]); w.y = pkh(r[2], r[3]); w.z = pkh(r[4], r[5]); w.w = pkh(r[6], r[7]);
;                 *(u32x4*)rowp = w;
;                 w.x = pkh(sg[0], sg[1]); w.y = pkh(sg[2], sg[3]); w.z = pkh(sg[4], sg[5]); w.w = pkh(sg[6], sg[7]);
;                 *(u32x4*)(rowp + 32768) = w; }
	v_mul_f32_e32 v18, 0xbfb8aa3b, v18
	v_mul_f32_e32 v19, 0xbfb8aa3b, v19
	v_mul_f32_e32 v21, 0xbfb8aa3b, v21
	v_exp_f32_e32 v18, v18
	v_exp_f32_e32 v19, v19
	v_exp_f32_e32 v21, v21
	v_fmamk_f32 v23, v102, 0x3a000000, v10
	v_mul_f32_e32 v23, 0xbfb8aa3b, v23
	v_fmamk_f32 v22, v110, 0x3a000000, v14
	v_exp_f32_e32 v24, v23
	v_fmamk_f32 v23, v111, 0x3a000000, v15
	v_fmamk_f32 v25, v103, 0x3a000000, v11
	v_mul_f32_e32 v27, 0xbfb8aa3b, v27
	v_mul_f32_e32 v22, 0xbfb8aa3b, v22
	v_mul_f32_e32 v23, 0xbfb8aa3b, v23
	v_mul_f32_e32 v25, 0xbfb8aa3b, v25
	v_fmamk_f32 v26, v104, 0x3a000000, v4
	v_exp_f32_e32 v28, v27
	v_fmamk_f32 v27, v105, 0x3a000000, v5
	v_fmamk_f32 v29, v97, 0x3a000000, v1
	v_pk_add_f32 v[20:21], v[20:21], 1.0 op_sel_hi:[1,0]
	v_pk_add_f32 v[18:19], v[18:19], 1.0 op_sel_hi:[1,0]
	v_exp_f32_e32 v22, v22
	v_exp_f32_e32 v23, v23
	v_exp_f32_e32 v25, v25
	v_mul_f32_e32 v26, 0xbfb8aa3b, v26
	v_mul_f32_e32 v27, 0xbfb8aa3b, v27
	v_mul_f32_e32 v29, 0xbfb8aa3b, v29
	v_fmamk_f32 v31, v98, 0x3a000000, v2
	v_fmamk_f32 v97, v99, 0x3a000000, v3
	v_pk_mul_f32 v[98:99], v[20:21], v[20:21]
	v_pk_mul_f32 v[20:21], v[18:19], v[20:21]
	v_exp_f32_e32 v26, v26
	v_exp_f32_e32 v27, v27
	v_exp_f32_e32 v29, v29
	v_rcp_f32_e32 v20, v20
	v_rcp_f32_e32 v21, v21
	v_mul_f32_e32 v31, 0xbfb8aa3b, v31
	v_pk_add_f32 v[24:25], v[24:25], 1.0 op_sel_hi:[1,0]
	v_pk_add_f32 v[108:109], v[22:23], 1.0 op_sel_hi:[1,0]
	v_fmamk_f32 v30, v106, 0x3a000000, v6
	v_exp_f32_e32 v96, v31
	v_fmamk_f32 v31, v107, 0x3a000000, v7
	v_pk_add_f32 v[28:29], v[28:29], 1.0 op_sel_hi:[1,0]
	v_pk_mul_f32 v[106:107], v[18:19], v[20:21]
	v_pk_mul_f32 v[18:19], v[108:109], v[24:25]
	v_pk_add_f32 v[26:27], v[26:27], 1.0 op_sel_hi:[1,0]
	v_mul_f32_e32 v30, 0xbfb8aa3b, v30
	v_mul_f32_e32 v31, 0xbfb8aa3b, v31
	v_mul_f32_e32 v97, 0xbfb8aa3b, v97
	v_pk_mul_f32 v[100:101], v[24:25], v[24:25]
	v_pk_mul_f32 v[102:103], v[28:29], v[28:29]
	v_rcp_f32_e32 v24, v18
	v_rcp_f32_e32 v25, v19
	v_pk_mul_f32 v[28:29], v[26:27], v[28:29]
	v_exp_f32_e32 v30, v30
	v_exp_f32_e32 v31, v31
	v_exp_f32_e32 v97, v97
	v_rcp_f32_e32 v28, v28
	v_rcp_f32_e32 v29, v29
	v_pk_mul_f32 v[18:19], v[98:99], v[20:21]
	v_pk_mul_f32 v[20:21], v[108:109], v[24:25]
	v_pk_mul_f32 v[24:25], v[100:101], v[24:25]
	v_pk_add_f32 v[96:97], v[96:97], 1.0 op_sel_hi:[1,0]
	v_cvt_pk_f16_f32 v18, v18, v19
	v_cvt_pk_f16_f32 v19, v24, v25
	v_pk_mul_f32 v[24:25], v[26:27], v[28:29]
	v_pk_add_f32 v[26:27], v[30:31], 1.0 op_sel_hi:[1,0]
	v_cvt_pk_f16_f32 v23, v20, v21
	v_pk_mul_f32 v[20:21], v[26:27], v[96:97]
	v_pk_mul_f32 v[104:105], v[96:97], v[96:97]
	v_rcp_f32_e32 v30, v20
	v_rcp_f32_e32 v31, v21
	v_pk_mul_f32 v[20:21], v[102:103], v[28:29]
	v_cvt_pk_f16_f32 v22, v106, v107
	v_cvt_pk_f16_f32 v20, v20, v21
	v_pk_mul_f32 v[28:29], v[104:105], v[30:31]
	v_pk_mul_f32 v[26:27], v[26:27], v[30:31]
	v_cvt_pk_f16_f32 v21, v28, v29
	v_add_co_u32_e32 v28, vcc, s66, v16
	v_cvt_pk_f16_f32 v24, v24, v25
	s_nop 0
	v_addc_co_u32_e32 v29, vcc, 0, v17, vcc
	global_store_dwordx4 v[28:29], v[18:21], off nt
	v_cvt_pk_f16_f32 v25, v26, v27
	v_fmamk_f32 v27, v80, 0x3a000000, v0
	v_add_co_u32_e32 v18, vcc, s62, v16
	v_fmamk_f32 v21, v85, 0x3a000000, v9
	s_nop 0
	v_addc_co_u32_e32 v19, vcc, 0, v17, vcc
	global_store_dwordx4 v[18:19], v[22:25], off nt
	v_fmamk_f32 v19, v84, 0x3a000000, v8
	v_mul_f32_e32 v19, 0xbfb8aa3b, v19
	v_fmamk_f32 v18, v92, 0x3a000000, v12
	v_exp_f32_e32 v20, v19
	v_fmamk_f32 v19, v93, 0x3a000000, v13
	v_mul_f32_e32 v18, 0xbfb8aa3b, v18
	v_mul_f32_e32 v19, 0xbfb8aa3b, v19
	v_mul_f32_e32 v21, 0xbfb8aa3b, v21
	v_exp_f32_e32 v18, v18
	v_exp_f32_e32 v19, v19
	v_exp_f32_e32 v21, v21
	v_fmamk_f32 v23, v86, 0x3a000000, v10
	v_mul_f32_e32 v23, 0xbfb8aa3b, v23
	v_fmamk_f32 v22, v94, 0x3a000000, v14
	v_exp_f32_e32 v24, v23
	v_fmamk_f32 v23, v95, 0x3a000000, v15
	v_fmamk_f32 v25, v87, 0x3a000000, v11
	v_mul_f32_e32 v27, 0xbfb8aa3b, v27
	v_mul_f32_e32 v22, 0xbfb8aa3b, v22
	v_mul_f32_e32 v23, 0xbfb8aa3b, v23
	v_mul_f32_e32 v25, 0xbfb8aa3b, v25
	v_fmamk_f32 v26, v88, 0x3a000000, v4
	v_exp_f32_e32 v28, v27
	v_fmamk_f32 v27, v89, 0x3a000000, v5
	v_fmamk_f32 v29, v81, 0x3a000000, v1
	v_pk_add_f32 v[20:21], v[20:21], 1.0 op_sel_hi:[1,0]
	v_pk_add_f32 v[18:19], v[18:19], 1.0 op_sel_hi:[1,0]
	v_exp_f32_e32 v22, v22
	v_exp_f32_e32 v23, v23
	v_exp_f32_e32 v25, v25
	v_mul_f32_e32 v26, 0xbfb8aa3b, v26
	v_mul_f32_e32 v27, 0xbfb8aa3b, v27
	v_mul_f32_e32 v29, 0xbfb8aa3b, v29
	v_fmamk_f32 v31, v82, 0x3a000000, v2
	v_fmamk_f32 v81, v83, 0x3a000000, v3
	v_pk_mul_f32 v[82:83], v[20:21], v[20:21]
	v_pk_mul_f32 v[20:21], v[18:19], v[20:21]
	v_exp_f32_e32 v26, v26
	v_exp_f32_e32 v27, v27
	v_exp_f32_e32 v29, v29
	v_rcp_f32_e32 v20, v20
	v_rcp_f32_e32 v21, v21
	v_mul_f32_e32 v31, 0xbfb8aa3b, v31
	v_pk_add_f32 v[24:25], v[24:25], 1.0 op_sel_hi:[1,0]
	v_pk_add_f32 v[92:93], v[22:23], 1.0 op_sel_hi:[1,0]
	v_fmamk_f32 v30, v90, 0x3a000000, v6
	v_exp_f32_e32 v80, v31
	v_fmamk_f32 v31, v91, 0x3a000000, v7
	v_pk_add_f32 v[28:29], v[28:29], 1.0 op_sel_hi:[1,0]
	v_pk_mul_f32 v[90:91], v[18:19], v[20:21]
	v_pk_mul_f32 v[18:19], v[92:93], v[24:25]
	v_pk_add_f32 v[26:27], v[26:27], 1.0 op_sel_hi:[1,0]
	v_mul_f32_e32 v30, 0xbfb8aa3b, v30
	v_mul_f32_e32 v31, 0xbfb8aa3b, v31
	v_mul_f32_e32 v81, 0xbfb8aa3b, v81
	v_pk_mul_f32 v[84:85], v[24:25], v[24:25]
	v_pk_mul_f32 v[86:87], v[28:29], v[28:29]
	v_rcp_f32_e32 v24, v18
	v_rcp_f32_e32 v25, v19
	v_pk_mul_f32 v[28:29], v[26:27], v[28:29]
	v_exp_f32_e32 v30, v30
	v_exp_f32_e32 v31, v31
	v_exp_f32_e32 v81, v81
	v_rcp_f32_e32 v28, v28
	v_rcp_f32_e32 v29, v29
	v_pk_mul_f32 v[18:19], v[82:83], v[20:21]
	v_pk_mul_f32 v[20:21], v[92:93], v[24:25]
;     __device__ __forceinline__ void operator()(const f32x4 (&acc)[2][2][4][2], const Unit& u, int wr, int wc, int fr, int fq) const {
;         const int row0 = u.pm * BM + wr * 64 + fr;
;         const int c0 = u.pn * 128 + 32 * wc + 8 * fq;
;         constexpr float DS = 1.f / (F8_SU * F8_SW);
;         f32x4 ba[2], bb[2];
; #pragma unroll
;         for (int n = 0; n < 2; ++n) { ba[n] = *(const f32x4*)(gbias + c0 + 4 * n); bb[n] = *(const f32x4*)(gbias + D + c0 + 4 * n); }
; #pragma unroll
;         for (int ai = 0; ai < 2; ++ai)
; #pragma unroll
;             for (int m = 0; m < 4; ++m) {
;                 h16* rowp = PG + (size_t)(u.pm * 32 + u.pn) * 65536 + (ai * 4 + m) * 4096 + (wr * 4 + wc) * 512 + (fq * 16 + fr) * 8;
;                 float r[8], sg[8];
; #pragma unroll
;                 for (int n = 0; n < 2; ++n)
; #pragma unroll
;                     for (int j = 0; j < 4; ++j) { const float ea = __expf(-(acc[ai][0][m][n][j] * DS + ba[n][j])), eb = __expf(-(acc[ai][1][m][n][j] * DS + bb[n][j]));
;                         const float pa = 1.f + ea, pb = 1.f + eb, rp = __builtin_amdgcn_rcpf(pa * pb);
;                         sg[4 * n + j] = pa * rp; r[4 * n + j] = pb * pb * rp; }
;                 u32x4 w; w.x = pkh(r[0], r[1]); w.y = pkh(r[2], r[3]); w.z = pkh(r[4], r[5]); w.w = pkh(r[6], r[7]);
;                 *(u32x4*)rowp = w;
;                 w.x = pkh(sg[0], sg[1]); w.y = pkh(sg[2], sg[3]); w.z = pkh(sg[4], sg[5]); w.w = pkh(sg[6], sg[7]);
;                 *(u32x4*)(rowp + 32768) = w; }
	v_pk_mul_f32 v[24:25], v[84:85], v[24:25]
	v_pk_add_f32 v[80:81], v[80:81], 1.0 op_sel_hi:[1,0]
	v_cvt_pk_f16_f32 v18, v18, v19
	v_cvt_pk_f16_f32 v19, v24, v25
	v_pk_mul_f32 v[24:25], v[26:27], v[28:29]
	v_pk_add_f32 v[26:27], v[30:31], 1.0 op_sel_hi:[1,0]
	v_cvt_pk_f16_f32 v23, v20, v21
	v_pk_mul_f32 v[20:21], v[26:27], v[80:81]
	v_pk_mul_f32 v[88:89], v[80:81], v[80:81]
	v_rcp_f32_e32 v30, v20
	v_rcp_f32_e32 v31, v21
	v_pk_mul_f32 v[20:21], v[86:87], v[28:29]
	v_cvt_pk_f16_f32 v22, v90, v91
	v_cvt_pk_f16_f32 v20, v20, v21
	v_pk_mul_f32 v[28:29], v[88:89], v[30:31]
	v_pk_mul_f32 v[26:27], v[26:27], v[30:31]
	v_cvt_pk_f16_f32 v21, v28, v29
	v_add_co_u32_e32 v28, vcc, s71, v16
	v_cvt_pk_f16_f32 v24, v24, v25
	s_nop 0
	v_addc_co_u32_e32 v29, vcc, 0, v17, vcc
	global_store_dwordx4 v[28:29], v[18:21], off nt
	v_cvt_pk_f16_f32 v25, v26, v27
	v_fmamk_f32 v27, v64, 0x3a000000, v0
	v_add_co_u32_e32 v18, vcc, s69, v16
	v_fmamk_f32 v21, v69, 0x3a000000, v9
	s_nop 0
	v_addc_co_u32_e32 v19, vcc, 0, v17, vcc
	global_store_dwordx4 v[18:19], v[22:25], off nt
	v_fmamk_f32 v19, v68, 0x3a000000, v8
	v_mul_f32_e32 v19, 0xbfb8aa3b, v19
	v_fmamk_f32 v18, v76, 0x3a000000, v12
	v_exp_f32_e32 v20, v19
	v_fmamk_f32 v19, v77, 0x3a000000, v13
	v_mul_f32_e32 v18, 0xbfb8aa3b, v18
	v_mul_f32_e32 v19, 0xbfb8aa3b, v19
	v_mul_f32_e32 v21, 0xbfb8aa3b, v21
	v_exp_f32_e32 v18, v18
	v_exp_f32_e32 v19, v19
	v_exp_f32_e32 v21, v21
	v_fmamk_f32 v23, v70, 0x3a000000, v10
	v_mul_f32_e32 v23, 0xbfb8aa3b, v23
	v_fmamk_f32 v22, v78, 0x3a000000, v14
	v_exp_f32_e32 v24, v23
	v_fmamk_f32 v23, v79, 0x3a000000, v15
	v_fmamk_f32 v25, v71, 0x3a000000, v11
	v_mul_f32_e32 v27, 0xbfb8aa3b, v27
	v_mul_f32_e32 v22, 0xbfb8aa3b, v22
	v_mul_f32_e32 v23, 0xbfb8aa3b, v23
	v_mul_f32_e32 v25, 0xbfb8aa3b, v25
	v_fmamk_f32 v26, v72, 0x3a000000, v4
	v_exp_f32_e32 v28, v27
	v_fmamk_f32 v27, v73, 0x3a000000, v5
	v_fmamk_f32 v29, v65, 0x3a000000, v1
	v_pk_add_f32 v[20:21], v[20:21], 1.0 op_sel_hi:[1,0]
	v_pk_add_f32 v[18:19], v[18:19], 1.0 op_sel_hi:[1,0]
	v_exp_f32_e32 v22, v22
	v_exp_f32_e32 v23, v23
	v_exp_f32_e32 v25, v25
	v_mul_f32_e32 v26, 0xbfb8aa3b, v26
	v_mul_f32_e32 v27, 0xbfb8aa3b, v27
	v_mul_f32_e32 v29, 0xbfb8aa3b, v29
	v_fmamk_f32 v31, v66, 0x3a000000, v2
	v_fmamk_f32 v65, v67, 0x3a000000, v3
	v_pk_mul_f32 v[66:67], v[20:21], v[20:21]
	v_pk_mul_f32 v[20:21], v[18:19], v[20:21]
	v_exp_f32_e32 v26, v26
	v_exp_f32_e32 v27, v27
	v_exp_f32_e32 v29, v29
	v_rcp_f32_e32 v20, v20
	v_rcp_f32_e32 v21, v21
	v_mul_f32_e32 v31, 0xbfb8aa3b, v31
	v_pk_add_f32 v[24:25], v[24:25], 1.0 op_sel_hi:[1,0]
	v_pk_add_f32 v[76:77], v[22:23], 1.0 op_sel_hi:[1,0]
	v_fmamk_f32 v30, v74, 0x3a000000, v6
	v_exp_f32_e32 v64, v31
	v_fmamk_f32 v31, v75, 0x3a000000, v7
	v_pk_add_f32 v[28:29], v[28:29], 1.0 op_sel_hi:[1,0]
	v_pk_mul_f32 v[74:75], v[18:19], v[20:21]
	v_pk_mul_f32 v[18:19], v[76:77], v[24:25]
	v_pk_add_f32 v[26:27], v[26:27], 1.0 op_sel_hi:[1,0]
	v_mul_f32_e32 v30, 0xbfb8aa3b, v30
	v_mul_f32_e32 v31, 0xbfb8aa3b, v31
	v_mul_f32_e32 v65, 0xbfb8aa3b, v65
	v_pk_mul_f32 v[68:69], v[24:25], v[24:25]
	v_pk_mul_f32 v[70:71], v[28:29], v[28:29]
	v_rcp_f32_e32 v24, v18
	v_rcp_f32_e32 v25, v19
	v_pk_mul_f32 v[28:29], v[26:27], v[28:29]
	v_exp_f32_e32 v30, v30
	v_exp_f32_e32 v31, v31
	v_exp_f32_e32 v65, v65
	v_rcp_f32_e32 v28, v28
	v_rcp_f32_e32 v29, v29
	v_pk_mul_f32 v[18:19], v[66:67], v[20:21]
	v_pk_mul_f32 v[20:21], v[76:77], v[24:25]
	v_pk_mul_f32 v[24:25], v[68:69], v[24:25]
	v_pk_add_f32 v[64:65], v[64:65], 1.0 op_sel_hi:[1,0]
	v_cvt_pk_f16_f32 v18, v18, v19
	v_cvt_pk_f16_f32 v19, v24, v25
	v_pk_mul_f32 v[24:25], v[26:27], v[28:29]
	v_pk_add_f32 v[26:27], v[30:31], 1.0 op_sel_hi:[1,0]
	v_cvt_pk_f16_f32 v23, v20, v21
	v_pk_mul_f32 v[20:21], v[26:27], v[64:65]
	v_pk_mul_f32 v[72:73], v[64:65], v[64:65]
	v_rcp_f32_e32 v30, v20
	v_rcp_f32_e32 v31, v21
	v_pk_mul_f32 v[20:21], v[70:71], v[28:29]
	v_cvt_pk_f16_f32 v22, v74, v75
	v_cvt_pk_f16_f32 v20, v20, v21
	v_pk_mul_f32 v[28:29], v[72:73], v[30:31]
	v_pk_mul_f32 v[26:27], v[26:27], v[30:31]
	v_cvt_pk_f16_f32 v21, v28, v29
	v_add_co_u32_e32 v28, vcc, s72, v16
	v_cvt_pk_f16_f32 v24, v24, v25
	s_nop 0
	v_addc_co_u32_e32 v29, vcc, 0, v17, vcc
	global_store_dwordx4 v[28:29], v[18:21], off nt
	v_cvt_pk_f16_f32 v25, v26, v27
	v_fmamk_f32 v27, v48, 0x3a000000, v0
	v_add_co_u32_e32 v18, vcc, s70, v16
	v_fmamk_f32 v21, v53, 0x3a000000, v9
	s_nop 0
	v_addc_co_u32_e32 v19, vcc, 0, v17, vcc
	global_store_dwordx4 v[18:19], v[22:25], off nt
	v_fmamk_f32 v19, v52, 0x3a000000, v8
	v_mul_f32_e32 v19, 0xbfb8aa3b, v19
	v_fmamk_f32 v18, v60, 0x3a000000, v12
	v_exp_f32_e32 v20, v19
	v_fmamk_f32 v19, v61, 0x3a000000, v13
	v_mul_f32_e32 v18, 0xbfb8aa3b, v18
	v_mul_f32_e32 v19, 0xbfb8aa3b, v19
	v_mul_f32_e32 v21, 0xbfb8aa3b, v21
	v_exp_f32_e32 v18, v18
	v_exp_f32_e32 v19, v19
	v_exp_f32_e32 v21, v21
	v_fmamk_f32 v23, v54, 0x3a000000, v10
	v_mul_f32_e32 v23, 0xbfb8aa3b, v23
	v_fmamk_f32 v22, v62, 0x3a000000, v14
	v_exp_f32_e32 v24, v23
	v_fmamk_f32 v23, v63, 0x3a000000, v15
	v_fmamk_f32 v25, v55, 0x3a000000, v11
	v_mul_f32_e32 v27, 0xbfb8aa3b, v27
	v_mul_f32_e32 v22, 0xbfb8aa3b, v22
	v_mul_f32_e32 v23, 0xbfb8aa3b, v23
	v_mul_f32_e32 v25, 0xbfb8aa3b, v25
	v_fmamk_f32 v26, v56, 0x3a000000, v4
	v_exp_f32_e32 v28, v27
	v_fmamk_f32 v27, v57, 0x3a000000, v5
	v_fmamk_f32 v29, v49, 0x3a000000, v1
	v_pk_add_f32 v[20:21], v[20:21], 1.0 op_sel_hi:[1,0]
	v_pk_add_f32 v[18:19], v[18:19], 1.0 op_sel_hi:[1,0]
	v_exp_f32_e32 v22, v22
	v_exp_f32_e32 v23, v23
	v_exp_f32_e32 v25, v25
	v_mul_f32_e32 v26, 0xbfb8aa3b, v26
	v_mul_f32_e32 v27, 0xbfb8aa3b, v27
	v_mul_f32_e32 v29, 0xbfb8aa3b, v29
;     __device__ __forceinline__ void operator()(const f32x4 (&acc)[2][2][4][2], const Unit& u, int wr, int wc, int fr, int fq) const {
;         const int row0 = u.pm * BM + wr * 64 + fr;
;         const int c0 = u.pn * 128 + 32 * wc + 8 * fq;
;         constexpr float DS = 1.f / (F8_SU * F8_SW);
;         f32x4 ba[2], bb[2];
; #pragma unroll
;         for (int n = 0; n < 2; ++n) { ba[n] = *(const f32x4*)(gbias + c0 + 4 * n); bb[n] = *(const f32x4*)(gbias + D + c0 + 4 * n); }
; #pragma unroll
;         for (int ai = 0; ai < 2; ++ai)
; #pragma unroll
;             for (int m = 0; m < 4; ++m) {
;                 h16* rowp = PG + (size_t)(u.pm * 32 + u.pn) * 65536 + (ai * 4 + m) * 4096 + (wr * 4 + wc) * 512 + (fq * 16 + fr) * 8;
;                 float r[8], sg[8];
; #pragma unroll
;                 for (int n = 0; n < 2; ++n)
; #pragma unroll
;                     for (int j = 0; j < 4; ++j) { const float ea = __expf(-(acc[ai][0][m][n][j] * DS + ba[n][j])), eb = __expf(-(acc[ai][1][m][n][j] * DS + bb[n][j]));
;                         const float pa = 1.f + ea, pb = 1.f + eb, rp = __builtin_amdgcn_rcpf(pa * pb);
;                         sg[4 * n + j] = pa * rp; r[4 * n + j] = pb * pb * rp; }
;                 u32x4 w; w.x = pkh(r[0], r[1]); w.y = pkh(r[2], r[3]); w.z = pkh(r[4], r[5]); w.w = pkh(r[6], r[7]);
;                 *(u32x4*)rowp = w;
;                 w.x = pkh(sg[0], sg[1]); w.y = pkh(sg[2], sg[3]); w.z = pkh(sg[4], sg[5]); w.w = pkh(sg[6], sg[7]);
;                 *(u32x4*)(rowp + 32768) = w; }
	v_fmamk_f32 v31, v50, 0x3a000000, v2
	v_fmamk_f32 v49, v51, 0x3a000000, v3
	v_pk_mul_f32 v[50:51], v[20:21], v[20:21]
	v_pk_mul_f32 v[20:21], v[18:19], v[20:21]
	v_exp_f32_e32 v26, v26
	v_exp_f32_e32 v27, v27
	v_exp_f32_e32 v29, v29
	v_rcp_f32_e32 v20, v20
	v_rcp_f32_e32 v21, v21
	v_mul_f32_e32 v31, 0xbfb8aa3b, v31
	v_pk_add_f32 v[24:25], v[24:25], 1.0 op_sel_hi:[1,0]
	v_pk_add_f32 v[60:61], v[22:23], 1.0 op_sel_hi:[1,0]
	v_fmamk_f32 v30, v58, 0x3a000000, v6
	v_exp_f32_e32 v48, v31
	v_fmamk_f32 v31, v59, 0x3a000000, v7
	v_pk_add_f32 v[28:29], v[28:29], 1.0 op_sel_hi:[1,0]
	v_pk_mul_f32 v[58:59], v[18:19], v[20:21]
	v_pk_mul_f32 v[18:19], v[60:61], v[24:25]
	v_pk_add_f32 v[26:27], v[26:27], 1.0 op_sel_hi:[1,0]
	v_mul_f32_e32 v30, 0xbfb8aa3b, v30
	v_mul_f32_e32 v31, 0xbfb8aa3b, v31
	v_mul_f32_e32 v49, 0xbfb8aa3b, v49
	v_pk_mul_f32 v[52:53], v[24:25], v[24:25]
	v_pk_mul_f32 v[54:55], v[28:29], v[28:29]
	v_rcp_f32_e32 v24, v18
	v_rcp_f32_e32 v25, v19
	v_pk_mul_f32 v[28:29], v[26:27], v[28:29]
	v_exp_f32_e32 v30, v30
	v_exp_f32_e32 v31, v31
	v_exp_f32_e32 v49, v49
	v_rcp_f32_e32 v28, v28
	v_rcp_f32_e32 v29, v29
	v_pk_mul_f32 v[18:19], v[50:51], v[20:21]
	v_pk_mul_f32 v[20:21], v[60:61], v[24:25]
	v_pk_mul_f32 v[24:25], v[52:53], v[24:25]
	v_pk_add_f32 v[48:49], v[48:49], 1.0 op_sel_hi:[1,0]
	v_cvt_pk_f16_f32 v18, v18, v19
	v_cvt_pk_f16_f32 v19, v24, v25
	v_pk_mul_f32 v[24:25], v[26:27], v[28:29]
	v_pk_add_f32 v[26:27], v[30:31], 1.0 op_sel_hi:[1,0]
	v_cvt_pk_f16_f32 v23, v20, v21
	v_pk_mul_f32 v[20:21], v[26:27], v[48:49]
	v_pk_mul_f32 v[56:57], v[48:49], v[48:49]
	v_rcp_f32_e32 v30, v20
	v_rcp_f32_e32 v31, v21
	v_pk_mul_f32 v[20:21], v[54:55], v[28:29]
	v_fmamk_f32 v4, v40, 0x3a000000, v4
	v_cvt_pk_f16_f32 v20, v20, v21
	v_pk_mul_f32 v[28:29], v[56:57], v[30:31]
	v_pk_mul_f32 v[26:27], v[26:27], v[30:31]
	v_cvt_pk_f16_f32 v21, v28, v29
	v_add_co_u32_e32 v28, vcc, s76, v16
	v_cvt_pk_f16_f32 v22, v58, v59
	s_nop 0
	v_addc_co_u32_e32 v29, vcc, 0, v17, vcc
	global_store_dwordx4 v[28:29], v[18:21], off nt
	v_cvt_pk_f16_f32 v24, v24, v25
	v_cvt_pk_f16_f32 v25, v26, v27
	v_add_co_u32_e32 v18, vcc, s73, v16
	v_fmamk_f32 v12, v44, 0x3a000000, v12
	s_nop 0
	v_addc_co_u32_e32 v19, vcc, 0, v17, vcc
	v_fmamk_f32 v8, v36, 0x3a000000, v8
	v_fmamk_f32 v13, v45, 0x3a000000, v13
	v_fmamk_f32 v9, v37, 0x3a000000, v9
	v_mul_f32_e32 v4, 0xbfb8aa3b, v4
	v_fmamk_f32 v0, v32, 0x3a000000, v0
	v_fmamk_f32 v1, v33, 0x3a000000, v1
	global_store_dwordx4 v[18:19], v[22:25], off nt
	v_mul_f32_e32 v12, 0xbfb8aa3b, v12
	v_mul_f32_e32 v8, 0xbfb8aa3b, v8
	v_mul_f32_e32 v13, 0xbfb8aa3b, v13
	v_mul_f32_e32 v9, 0xbfb8aa3b, v9
	v_exp_f32_e32 v18, v4
	v_mul_f32_e32 v0, 0xbfb8aa3b, v0
	v_fmamk_f32 v4, v41, 0x3a000000, v5
	v_mul_f32_e32 v1, 0xbfb8aa3b, v1
	v_exp_f32_e32 v12, v12
	v_exp_f32_e32 v8, v8
	v_exp_f32_e32 v13, v13
	v_exp_f32_e32 v9, v9
	v_exp_f32_e32 v0, v0
	v_mul_f32_e32 v4, 0xbfb8aa3b, v4
	v_exp_f32_e32 v1, v1
	v_exp_f32_e32 v19, v4
	v_fmamk_f32 v4, v42, 0x3a000000, v6
	v_mul_f32_e32 v4, 0xbfb8aa3b, v4
	v_fmac_f32_e32 v7, 0x3a000000, v43
	v_fmamk_f32 v14, v46, 0x3a000000, v14
	v_fmamk_f32 v10, v38, 0x3a000000, v10
	v_fmac_f32_e32 v15, 0x3a000000, v47
	v_fmac_f32_e32 v11, 0x3a000000, v39
	v_exp_f32_e32 v6, v4
	v_mul_f32_e32 v4, 0xbfb8aa3b, v7
	v_mul_f32_e32 v14, 0xbfb8aa3b, v14
	v_mul_f32_e32 v10, 0xbfb8aa3b, v10
	v_mul_f32_e32 v15, 0xbfb8aa3b, v15
	v_mul_f32_e32 v11, 0xbfb8aa3b, v11
	v_exp_f32_e32 v7, v4
	v_pk_add_f32 v[4:5], v[8:9], 1.0 op_sel_hi:[1,0]
	v_pk_add_f32 v[22:23], v[0:1], 1.0 op_sel_hi:[1,0]
	v_pk_add_f32 v[0:1], v[12:13], 1.0 op_sel_hi:[1,0]
	v_exp_f32_e32 v14, v14
	v_exp_f32_e32 v10, v10
	v_exp_f32_e32 v15, v15
	v_exp_f32_e32 v11, v11
	v_pk_mul_f32 v[8:9], v[4:5], v[4:5]
	v_pk_mul_f32 v[4:5], v[0:1], v[4:5]
	v_pk_add_f32 v[14:15], v[14:15], 1.0 op_sel_hi:[1,0]
	v_rcp_f32_e32 v4, v4
	v_rcp_f32_e32 v5, v5
	v_pk_add_f32 v[10:11], v[10:11], 1.0 op_sel_hi:[1,0]
	v_fmamk_f32 v2, v34, 0x3a000000, v2
	v_pk_mul_f32 v[20:21], v[10:11], v[10:11]
	v_pk_mul_f32 v[26:27], v[0:1], v[4:5]
	v_pk_mul_f32 v[0:1], v[14:15], v[10:11]
	v_fmac_f32_e32 v3, 0x3a000000, v35
	v_rcp_f32_e32 v10, v0
	v_rcp_f32_e32 v11, v1
	v_mul_f32_e32 v2, 0xbfb8aa3b, v2
	v_mul_f32_e32 v3, 0xbfb8aa3b, v3
	v_exp_f32_e32 v2, v2
	v_exp_f32_e32 v3, v3
	v_pk_mul_f32 v[0:1], v[8:9], v[4:5]
	v_pk_mul_f32 v[8:9], v[14:15], v[10:11]
	v_pk_add_f32 v[14:15], v[18:19], 1.0 op_sel_hi:[1,0]
	v_pk_mul_f32 v[10:11], v[20:21], v[10:11]
	v_pk_mul_f32 v[18:19], v[14:15], v[22:23]
	v_pk_add_f32 v[2:3], v[2:3], 1.0 op_sel_hi:[1,0]
	v_rcp_f32_e32 v18, v18
	v_rcp_f32_e32 v19, v19
	v_cvt_pk_f16_f32 v0, v0, v1
	v_cvt_pk_f16_f32 v1, v10, v11
	v_pk_add_f32 v[10:11], v[6:7], 1.0 op_sel_hi:[1,0]
	v_pk_mul_f32 v[24:25], v[2:3], v[2:3]
	v_pk_mul_f32 v[2:3], v[10:11], v[2:3]
	v_cvt_pk_f16_f32 v5, v8, v9
	v_pk_mul_f32 v[8:9], v[14:15], v[18:19]
	v_rcp_f32_e32 v14, v2
	v_rcp_f32_e32 v15, v3
	v_pk_mul_f32 v[12:13], v[22:23], v[22:23]
	v_cvt_pk_f16_f32 v6, v8, v9
	v_pk_mul_f32 v[2:3], v[12:13], v[18:19]
	v_pk_mul_f32 v[8:9], v[10:11], v[14:15]
	v_pk_mul_f32 v[10:11], v[24:25], v[14:15]
	v_cvt_pk_f16_f32 v2, v2, v3
	v_cvt_pk_f16_f32 v3, v10, v11
	v_add_co_u32_e32 v10, vcc, 0xe000, v16
	v_cvt_pk_f16_f32 v4, v26, v27
	s_nop 0
	v_addc_co_u32_e32 v11, vcc, 0, v17, vcc
	global_store_dwordx4 v[10:11], v[0:3], off nt
	v_cvt_pk_f16_f32 v7, v8, v9
	s_nop 0
	v_add_co_u32_e32 v0, vcc, 0x1e000, v16
	s_nop 1
	v_addc_co_u32_e32 v1, vcc, 0, v17, vcc
	s_andn2_b64 vcc, exec, s[0:1]
	s_mov_b64 s[0:1], -1
	global_store_dwordx4 v[0:1], v[4:7], off nt
	s_cbranch_vccnz .LBB0_149
	s_andn2_b64 vcc, exec, s[4:5]
	s_cbranch_vccnz .LBB0_148
	s_barrier
	s_branch .LBB0_148
